# up epilogue: the two in-lane conv FMAs of each token pair fused into one v_pk_fma_f32 (operand halves swapped through op_sel), 32 fewer VALU ops per block
# speedup vs baseline: 1.0642x; 1.0017x over previous
; DI int crow(int i, int h) { return (i & 3) + 8 * (i >> 2) + 4 * h; }
; template <int MB, class Epi>
; DI void gemm_tile(const u16* __restrict__ A, int lda, int row0, int Mrows, const u16* __restrict__ Bt, int ldb, int K, char* smem, Epi& epi, int rot) {
;     ...
;   const u16* bp = Bt + (size_t)lr * ldb + lch * 8;
;   f32x16 acc[2][MB];
; #pragma unroll
;   for (int nb = 0; nb < 2; ++nb)
; #pragma unroll
;     for (int mb = 0; mb < MB; ++mb)
; #pragma unroll
;       for (int i = 0; i < 16; ++i) acc[nb][mb][i] = 0.f;
;   const int KT = K >> 6;
;   int kcur = rot % KT;
;     ...
;   GEMM_STAGE(0)
;   asm volatile("s_waitcnt vmcnt(0)" ::: "memory");
;   __syncthreads();
;   const int sw = (r >> 1) & 7;
;   int foff[4];
; #pragma unroll
;   for (int ks = 0; ks < 4; ++ks) foff[ks] = r * 128 + (((2 * ks + h) ^ sw) << 4);
;   bf8 af[2][MB], bfr[2][2];
;   {
;     const char* as0 = As + wm * (32 * MB) * 128;
;     const char* bs0 = Bs + wn * 64 * 128;
; #pragma unroll
;     for (int mb = 0; mb < MB; ++mb) af[0][mb] = *(const bf8*)(as0 + mb * 32 * 128 + foff[0]);
; #pragma unroll
;     for (int nb = 0; nb < 2; ++nb) bfr[0][nb] = *(const bf8*)(bs0 + nb * 32 * 128 + foff[0]);
;   }
;   DI void operator()(f32x16 (&acc)[2][4], int wm, int wn, int r, int h) {
;     ...
;             const int ff = nt * 128 + wn * 32 + crow(i0, h) + nb * DFF;
;             const f32x2n a0 = *(const f32x2n*)(cw + ff), a1 = *(const f32x2n*)(cw + 2 * DFF + ff), a2 = *(const f32x2n*)(cw + 4 * DFF + ff),
;                          a3 = *(const f32x2n*)(cb + ff);
;             w0[0] = a0.x; w0[1] = a0.y; w1[0] = a1.x; w1[1] = a1.y; w2[0] = a2.x; w2[1] = a2.y; bz[0] = a3.x; bz[1] = a3.y;
.Lupd_w0:
	s_barrier
	v_bitop3_b32 v7, v169, v2, 2 bitop3:0x36
	ds_read_b128 v[146:149], v164
	ds_read_b128 v[142:145], v164 offset:4096
	ds_read_b128 v[134:137], v164 offset:8192
	ds_read_b128 v[130:133], v164 offset:12288
	s_add_u32 s28, s84, s28
	v_lshl_or_b32 v171, v7, 4, v3
	v_bitop3_b32 v7, v169, v2, 4 bitop3:0x36
	v_bitop3_b32 v2, v169, v2, 6 bitop3:0x36
	v_or_b32_e32 v166, s2, v5
	s_addc_u32 s29, s85, s29
	v_lshl_or_b32 v170, v7, 4, v3
	v_lshl_or_b32 v168, v2, 4, v3
	ds_read_b128 v[150:153], v166
	ds_read_b128 v[138:141], v166 offset:4096
	s_lshl_b32 s100, s48, 9
	s_lshl_b32 s101, s16, 7
	s_add_i32 s100, s100, s101
	v_lshlrev_b32_e32 v248, 2, v167
	v_add_u32_e32 v248, s100, v248
	v_add_u32_e32 v249, 0x2c00, v248
	global_load_dword v241, v248, s[40:41]
	global_load_dword v242, v248, s[44:45]
	global_load_dword v240, v248, s[46:47]
	global_load_dword v244, v248, s[42:43]
	global_load_dword v247, v249, s[40:41]
	global_load_dword v250, v249, s[44:45]
	global_load_dword v246, v249, s[46:47]
	global_load_dword v252, v249, s[42:43]
	s_add_i32 s25, s3, 0x8000
	v_lshl_add_u64 v[2:3], s[28:29], 0, v[0:1]
	s_mov_b32 m0, s25
	s_nop 0
	global_load_lds_dwordx4 v[2:3], off
	v_lshl_add_u64 v[2:3], s[28:29], 0, v[10:11]
	s_add_i32 s25, s3, 0xa000
	s_mov_b32 m0, s25
	s_nop 0
	global_load_lds_dwordx4 v[2:3], off
	v_lshl_add_u64 v[2:3], s[28:29], 0, v[12:13]
	s_add_i32 s25, s3, 0xc000
	s_mov_b32 m0, s25
	s_nop 0
	global_load_lds_dwordx4 v[2:3], off
	v_mov_b32_e32 v2, 0
	s_mov_b32 s18, 0
	v_lshl_add_u64 v[156:157], s[84:85], 0, v[14:15]
	v_lshlrev_b32_e32 v0, 1, v4
	v_lshlrev_b32_e32 v158, 1, v6
	v_lshlrev_b32_e32 v160, 1, v8
	s_mov_b32 s25, s19
	v_mov_b32_e32 v3, v2
	v_mov_b32_e32 v4, v2
	v_mov_b32_e32 v5, v2
	v_mov_b32_e32 v6, v2
	v_mov_b32_e32 v7, v2
	v_mov_b32_e32 v8, v2
	v_mov_b32_e32 v9, v2
	v_mov_b32_e32 v10, v2
	v_mov_b32_e32 v11, v2
	v_mov_b32_e32 v12, v2
	v_mov_b32_e32 v13, v2
	v_mov_b32_e32 v14, v2
	v_mov_b32_e32 v15, v2
	v_mov_b32_e32 v16, v2
	v_mov_b32_e32 v17, v2
	v_mov_b32_e32 v18, v2
	v_mov_b32_e32 v19, v2
	v_mov_b32_e32 v20, v2
	v_mov_b32_e32 v21, v2
	v_mov_b32_e32 v22, v2
	v_mov_b32_e32 v23, v2
	v_mov_b32_e32 v24, v2
	v_mov_b32_e32 v25, v2
	v_mov_b32_e32 v26, v2
	v_mov_b32_e32 v27, v2
	v_mov_b32_e32 v28, v2
	v_mov_b32_e32 v29, v2
	v_mov_b32_e32 v30, v2
	v_mov_b32_e32 v31, v2
	v_mov_b32_e32 v32, v2
	v_mov_b32_e32 v33, v2
	v_mov_b32_e32 v50, v2
	v_mov_b32_e32 v51, v2
	v_mov_b32_e32 v52, v2
	v_mov_b32_e32 v53, v2
	v_mov_b32_e32 v54, v2
	v_mov_b32_e32 v55, v2
	v_mov_b32_e32 v56, v2
	v_mov_b32_e32 v57, v2
	v_mov_b32_e32 v58, v2
	v_mov_b32_e32 v59, v2
	v_mov_b32_e32 v60, v2
	v_mov_b32_e32 v61, v2
	v_mov_b32_e32 v62, v2
	v_mov_b32_e32 v63, v2
	v_mov_b32_e32 v64, v2
	v_mov_b32_e32 v65, v2
	v_mov_b32_e32 v98, v2
	v_mov_b32_e32 v99, v2
	v_mov_b32_e32 v100, v2
	v_mov_b32_e32 v101, v2
	v_mov_b32_e32 v102, v2
	v_mov_b32_e32 v103, v2
	v_mov_b32_e32 v104, v2
	v_mov_b32_e32 v105, v2
	v_mov_b32_e32 v106, v2
	v_mov_b32_e32 v107, v2
	v_mov_b32_e32 v108, v2
	v_mov_b32_e32 v109, v2
	v_mov_b32_e32 v110, v2
	v_mov_b32_e32 v111, v2
	v_mov_b32_e32 v112, v2
	v_mov_b32_e32 v113, v2
	v_mov_b32_e32 v114, v2
	v_mov_b32_e32 v115, v2
	v_mov_b32_e32 v116, v2
	v_mov_b32_e32 v117, v2
	v_mov_b32_e32 v118, v2
	v_mov_b32_e32 v119, v2
	v_mov_b32_e32 v120, v2
	v_mov_b32_e32 v121, v2
	v_mov_b32_e32 v122, v2
	v_mov_b32_e32 v123, v2
	v_mov_b32_e32 v124, v2
	v_mov_b32_e32 v125, v2
	v_mov_b32_e32 v126, v2
	v_mov_b32_e32 v127, v2
	v_mov_b32_e32 v128, v2
	v_mov_b32_e32 v129, v2
	v_mov_b32_e32 v82, v2
	v_mov_b32_e32 v83, v2
	v_mov_b32_e32 v84, v2
	v_mov_b32_e32 v85, v2
	v_mov_b32_e32 v86, v2
	v_mov_b32_e32 v87, v2
	v_mov_b32_e32 v88, v2
	v_mov_b32_e32 v89, v2
	v_mov_b32_e32 v90, v2
	v_mov_b32_e32 v91, v2
	v_mov_b32_e32 v92, v2
	v_mov_b32_e32 v93, v2
	v_mov_b32_e32 v94, v2
	v_mov_b32_e32 v95, v2
	v_mov_b32_e32 v96, v2
	v_mov_b32_e32 v97, v2
	v_mov_b32_e32 v66, v2
	v_mov_b32_e32 v67, v2
	v_mov_b32_e32 v68, v2
	v_mov_b32_e32 v69, v2
	v_mov_b32_e32 v70, v2
	v_mov_b32_e32 v71, v2
	v_mov_b32_e32 v72, v2
	v_mov_b32_e32 v73, v2
	v_mov_b32_e32 v74, v2
	v_mov_b32_e32 v75, v2
	v_mov_b32_e32 v76, v2
	v_mov_b32_e32 v77, v2
	v_mov_b32_e32 v78, v2
	v_mov_b32_e32 v79, v2
	v_mov_b32_e32 v80, v2
	v_mov_b32_e32 v81, v2
	v_mov_b32_e32 v34, v2
	v_mov_b32_e32 v35, v2
	v_mov_b32_e32 v36, v2
	v_mov_b32_e32 v37, v2
	v_mov_b32_e32 v38, v2
	v_mov_b32_e32 v39, v2
	v_mov_b32_e32 v40, v2
	v_mov_b32_e32 v41, v2
	v_mov_b32_e32 v42, v2
	v_mov_b32_e32 v43, v2
	v_mov_b32_e32 v44, v2
	v_mov_b32_e32 v45, v2
	v_mov_b32_e32 v46, v2
	v_mov_b32_e32 v47, v2
	v_mov_b32_e32 v48, v2
	v_mov_b32_e32 v49, v2

; DI int crow(int i, int h) { return (i & 3) + 8 * (i >> 2) + 4 * h; }
;   DI void operator()(f32x16 (&acc)[2][4], int wm, int wn, int r, int h) {
;     ...
;             const int ff = nt * 128 + wn * 32 + crow(i0, h) + nb * DFF;
;             const f32x2n a0 = *(const f32x2n*)(cw + ff), a1 = *(const f32x2n*)(cw + 2 * DFF + ff), a2 = *(const f32x2n*)(cw + 4 * DFF + ff),
;                          a3 = *(const f32x2n*)(cb + ff);
;             w0[0] = a0.x; w0[1] = a0.y; w1[0] = a1.x; w1[1] = a1.y; w2[0] = a2.x; w2[1] = a2.y; bz[0] = a3.x; bz[1] = a3.y;
;           }
;           int spm = 0;
; #pragma unroll
;           for (int mb = 0; mb < 4; ++mb) {
;             const int spc = __builtin_amdgcn_ds_bpermute(sp << 2, xp[mb]);
;             const int snc = __builtin_amdgcn_ds_bpermute(sn << 2, xp[mb]);
;             const int snn = (mb < 3) ? __builtin_amdgcn_ds_bpermute(sn << 2, xp[mb < 3 ? mb + 1 : 3]) : 0;
;             const int pv = (mb > 0) ? ((r == 0) ? spm : spc) : spc;
;             const int nv = (mb < 3) ? ((r == 31) ? snn : snc) : snc;
;             float prev0 = __int_as_float(pv << 16), prev1 = __int_as_float(pv & 0xffff0000);
;             float next0 = __int_as_float(nv << 16), next1 = __int_as_float(nv & 0xffff0000);
;             if (mb == 0 && r == 0) { prev0 = eo0; prev1 = eo1; }
;             if (mb == 3 && r == 31) { next0 = eo0; next1 = eo1; }
;             spm = spc;
;             prev0 *= pm[mb]; prev1 *= pm[mb];
;             next0 *= nm[mb]; next1 *= nm[mb];
;             u[nb][mb][0] = w0[0] * prev0 + w1[0] * acc[nb][mb][i0] + w2[0] * next0 + bz[0];
;             u[nb][mb][1] = w0[1] * prev1 + w1[1] * acc[nb][mb][i0 + 1] + w2[1] * next1 + bz[1];
.Lupe_nb:
	s_cmp_lt_i32 s36, 0
	s_cbranch_scc0 .Lupe_slow
	v_mov_b32_e32 v184, v50
	v_mov_b32_e32 v185, v82
	v_pk_fma_f32 v[130:131], v[98:99], v[242:243], v[244:245] op_sel_hi:[1,0,0]
	v_pk_fma_f32 v[132:133], v[100:101], v[242:243], v[244:245] op_sel_hi:[1,0,0]
	v_pk_fma_f32 v[134:135], v[102:103], v[242:243], v[244:245] op_sel_hi:[1,0,0]
	v_pk_fma_f32 v[136:137], v[104:105], v[242:243], v[244:245] op_sel_hi:[1,0,0]
	v_pk_fma_f32 v[138:139], v[106:107], v[242:243], v[244:245] op_sel_hi:[1,0,0]
	v_pk_fma_f32 v[140:141], v[108:109], v[242:243], v[244:245] op_sel_hi:[1,0,0]
	v_pk_fma_f32 v[142:143], v[110:111], v[242:243], v[244:245] op_sel_hi:[1,0,0]
	v_pk_fma_f32 v[144:145], v[112:113], v[242:243], v[244:245] op_sel_hi:[1,0,0]
	v_pk_fma_f32 v[146:147], v[114:115], v[250:251], v[252:253] op_sel_hi:[1,0,0]
	v_pk_fma_f32 v[148:149], v[116:117], v[250:251], v[252:253] op_sel_hi:[1,0,0]
	v_pk_fma_f32 v[150:151], v[118:119], v[250:251], v[252:253] op_sel_hi:[1,0,0]
	v_pk_fma_f32 v[152:153], v[120:121], v[250:251], v[252:253] op_sel_hi:[1,0,0]
	v_pk_fma_f32 v[154:155], v[122:123], v[250:251], v[252:253] op_sel_hi:[1,0,0]
	v_pk_fma_f32 v[156:157], v[124:125], v[250:251], v[252:253] op_sel_hi:[1,0,0]
	v_pk_fma_f32 v[158:159], v[126:127], v[250:251], v[252:253] op_sel_hi:[1,0,0]
	v_pk_fma_f32 v[160:161], v[128:129], v[250:251], v[252:253] op_sel_hi:[1,0,0]
	v_pk_fma_f32 v[130:131], v[98:99], v[240:241], v[130:131] op_sel:[1,0,0] op_sel_hi:[0,1,1]
	v_pk_fma_f32 v[146:147], v[114:115], v[246:247], v[146:147] op_sel:[1,0,0] op_sel_hi:[0,1,1]
	v_pk_fma_f32 v[132:133], v[100:101], v[240:241], v[132:133] op_sel:[1,0,0] op_sel_hi:[0,1,1]
	v_pk_fma_f32 v[148:149], v[116:117], v[246:247], v[148:149] op_sel:[1,0,0] op_sel_hi:[0,1,1]
	v_pk_fma_f32 v[134:135], v[102:103], v[240:241], v[134:135] op_sel:[1,0,0] op_sel_hi:[0,1,1]
	v_pk_fma_f32 v[150:151], v[118:119], v[246:247], v[150:151] op_sel:[1,0,0] op_sel_hi:[0,1,1]
	v_pk_fma_f32 v[136:137], v[104:105], v[240:241], v[136:137] op_sel:[1,0,0] op_sel_hi:[0,1,1]
	v_pk_fma_f32 v[152:153], v[120:121], v[246:247], v[152:153] op_sel:[1,0,0] op_sel_hi:[0,1,1]
	v_pk_fma_f32 v[138:139], v[106:107], v[240:241], v[138:139] op_sel:[1,0,0] op_sel_hi:[0,1,1]
	v_pk_fma_f32 v[154:155], v[122:123], v[246:247], v[154:155] op_sel:[1,0,0] op_sel_hi:[0,1,1]
	v_pk_fma_f32 v[140:141], v[108:109], v[240:241], v[140:141] op_sel:[1,0,0] op_sel_hi:[0,1,1]
	v_pk_fma_f32 v[156:157], v[124:125], v[246:247], v[156:157] op_sel:[1,0,0] op_sel_hi:[0,1,1]
	v_pk_fma_f32 v[142:143], v[110:111], v[240:241], v[142:143] op_sel:[1,0,0] op_sel_hi:[0,1,1]
	v_pk_fma_f32 v[158:159], v[126:127], v[246:247], v[158:159] op_sel:[1,0,0] op_sel_hi:[0,1,1]
	v_pk_fma_f32 v[144:145], v[112:113], v[240:241], v[144:145] op_sel:[1,0,0] op_sel_hi:[0,1,1]
	v_pk_fma_f32 v[160:161], v[128:129], v[246:247], v[160:161] op_sel:[1,0,0] op_sel_hi:[0,1,1]
	v_permlane32_swap_b32_e32 v98, v101
	v_permlane32_swap_b32_e32 v102, v105
	v_permlane32_swap_b32_e32 v106, v109
	v_permlane32_swap_b32_e32 v110, v113
	v_permlane32_swap_b32_e32 v114, v117
	v_permlane32_swap_b32_e32 v118, v121
	v_permlane32_swap_b32_e32 v122, v125
	v_permlane32_swap_b32_e32 v126, v129
	v_permlane32_swap_b32_e32 v101, v102
	v_permlane32_swap_b32_e32 v105, v106
	v_permlane32_swap_b32_e32 v109, v110
	v_permlane32_swap_b32_e32 v117, v118
	v_permlane32_swap_b32_e32 v121, v122
	v_permlane32_swap_b32_e32 v125, v126
	v_permlane32_swap_b32_e32 v113, v184
	v_permlane32_swap_b32_e32 v129, v185
	s_waitcnt lgkmcnt(0)
	s_barrier
	s_mov_b32 s101, 0
	s_mov_b32 s2, s9

; DI unsigned pack2(float a, float b) { f2 v = {a, b}; bf2 r = __builtin_convertvector(v, bf2); return __builtin_bit_cast(unsigned, r); }
; DI float ex2(float x) { return __builtin_amdgcn_exp2f(x); }
; DI float gelu_tanh(float g) {
;   const float u = g * g;
;   const float t = g * (-2.302208198f - 0.1029432397f * u);
;   const float e = ex2(t);
;   return g * __builtin_amdgcn_rcpf(1.f + e);
; }
;   DI void operator()(f32x16 (&acc)[2][4], int wm, int wn, int r, int h) {
;     ...
;             float prev0 = __int_as_float(pv << 16), prev1 = __int_as_float(pv & 0xffff0000);
;             float next0 = __int_as_float(nv << 16), next1 = __int_as_float(nv & 0xffff0000);
;             if (mb == 0 && r == 0) { prev0 = eo0; prev1 = eo1; }
;             if (mb == 3 && r == 31) { next0 = eo0; next1 = eo1; }
;             spm = spc;
;             prev0 *= pm[mb]; prev1 *= pm[mb];
;             next0 *= nm[mb]; next1 *= nm[mb];
;             u[nb][mb][0] = w0[0] * prev0 + w1[0] * acc[nb][mb][i0] + w2[0] * next0 + bz[0];
;             u[nb][mb][1] = w0[1] * prev1 + w1[1] * acc[nb][mb][i0 + 1] + w2[1] * next1 + bz[1];
;           }
;         }
; #pragma unroll
;         for (int mb = 0; mb < 4; ++mb)
;           *(unsigned*)(ost + (mb * 32 + r) * 40 + ig * 8 + h * 4 + qp * 2) =
;               pack2(gelu_tanh(u[1][mb][0]) * u[0][mb][0], gelu_tanh(u[1][mb][1]) * u[0][mb][1]);
.Lupf_nonef:
	s_mov_b32 exec_hi, 0
	ds_read_b32 v98, v226 offset:256
	ds_read_b32 v114, v226 offset:384
	s_mov_b64 exec, -1
	v_fmac_f32_e32 v131, v240, v100
	v_fmac_f32_e32 v132, v241, v99
	v_fmac_f32_e32 v135, v240, v104
	v_fmac_f32_e32 v136, v241, v103
	v_fmac_f32_e32 v139, v240, v108
	v_fmac_f32_e32 v140, v241, v107
	v_fmac_f32_e32 v143, v240, v112
	v_fmac_f32_e32 v144, v241, v111
	v_fmac_f32_e32 v147, v246, v116
	v_fmac_f32_e32 v148, v247, v115
	v_fmac_f32_e32 v151, v246, v120
	v_fmac_f32_e32 v152, v247, v119
	v_fmac_f32_e32 v155, v246, v124
	v_fmac_f32_e32 v156, v247, v123
	v_fmac_f32_e32 v159, v246, v128
	v_fmac_f32_e32 v160, v247, v127
	s_waitcnt lgkmcnt(0)
	v_fmac_f32_e32 v130, v241, v98
	v_fmac_f32_e32 v133, v240, v101
	v_fmac_f32_e32 v134, v241, v102
	v_fmac_f32_e32 v137, v240, v105
	v_fmac_f32_e32 v138, v241, v106
	v_fmac_f32_e32 v141, v240, v109
	v_fmac_f32_e32 v142, v241, v110
	v_fmac_f32_e32 v145, v240, v113
	v_fmac_f32_e32 v146, v247, v114
	v_fmac_f32_e32 v149, v246, v117
	v_fmac_f32_e32 v150, v247, v118
	v_fmac_f32_e32 v153, v246, v121
	v_fmac_f32_e32 v154, v247, v122
	v_fmac_f32_e32 v157, v246, v125
	v_fmac_f32_e32 v158, v247, v126
	v_fmac_f32_e32 v161, v246, v129
	v_pk_mul_f32 v[188:189], v[146:147], v[146:147]
	v_pk_mul_f32 v[190:191], v[148:149], v[148:149]
	v_pk_mul_f32 v[192:193], v[150:151], v[150:151]
	v_pk_mul_f32 v[194:195], v[152:153], v[152:153]
	v_pk_mul_f32 v[196:197], v[154:155], v[154:155]
	v_pk_mul_f32 v[218:219], v[156:157], v[156:157]
	v_pk_mul_f32 v[220:221], v[158:159], v[158:159]
	v_pk_mul_f32 v[222:223], v[160:161], v[160:161]
	v_pk_fma_f32 v[188:189], v[188:189], v[178:179], v[180:181] op_sel_hi:[1,0,0]
	v_pk_fma_f32 v[190:191], v[190:191], v[178:179], v[180:181] op_sel_hi:[1,0,0]
	v_pk_fma_f32 v[192:193], v[192:193], v[178:179], v[180:181] op_sel_hi:[1,0,0]
	v_pk_fma_f32 v[194:195], v[194:195], v[178:179], v[180:181] op_sel_hi:[1,0,0]
	v_pk_fma_f32 v[196:197], v[196:197], v[178:179], v[180:181] op_sel_hi:[1,0,0]
	v_pk_fma_f32 v[218:219], v[218:219], v[178:179], v[180:181] op_sel_hi:[1,0,0]
	v_pk_fma_f32 v[220:221], v[220:221], v[178:179], v[180:181] op_sel_hi:[1,0,0]
	v_pk_fma_f32 v[222:223], v[222:223], v[178:179], v[180:181] op_sel_hi:[1,0,0]
	v_pk_mul_f32 v[188:189], v[146:147], v[188:189]
	v_pk_mul_f32 v[190:191], v[148:149], v[190:191]
	v_pk_mul_f32 v[192:193], v[150:151], v[192:193]
	v_pk_mul_f32 v[194:195], v[152:153], v[194:195]
	v_pk_mul_f32 v[196:197], v[154:155], v[196:197]
	v_pk_mul_f32 v[218:219], v[156:157], v[218:219]
	v_pk_mul_f32 v[220:221], v[158:159], v[220:221]
	v_pk_mul_f32 v[222:223], v[160:161], v[222:223]
	v_exp_f32_e32 v188, v188
	v_exp_f32_e32 v189, v189
	v_exp_f32_e32 v190, v190
	v_exp_f32_e32 v191, v191
	v_exp_f32_e32 v192, v192
	v_exp_f32_e32 v193, v193
	v_exp_f32_e32 v194, v194
	v_exp_f32_e32 v195, v195
	v_exp_f32_e32 v196, v196
	v_exp_f32_e32 v197, v197
	v_exp_f32_e32 v218, v218
	v_exp_f32_e32 v219, v219
	v_exp_f32_e32 v220, v220
	v_exp_f32_e32 v221, v221
	v_exp_f32_e32 v222, v222
	v_exp_f32_e32 v223, v223
	v_pk_add_f32 v[188:189], v[188:189], v[182:183] op_sel_hi:[1,0]
	v_pk_add_f32 v[190:191], v[190:191], v[182:183] op_sel_hi:[1,0]
	v_pk_add_f32 v[192:193], v[192:193], v[182:183] op_sel_hi:[1,0]
	v_pk_add_f32 v[194:195], v[194:195], v[182:183] op_sel_hi:[1,0]
	v_pk_add_f32 v[196:197], v[196:197], v[182:183] op_sel_hi:[1,0]
	v_pk_add_f32 v[218:219], v[218:219], v[182:183] op_sel_hi:[1,0]
	v_pk_add_f32 v[220:221], v[220:221], v[182:183] op_sel_hi:[1,0]
	v_pk_add_f32 v[222:223], v[222:223], v[182:183] op_sel_hi:[1,0]
	v_rcp_f32_e32 v188, v188
	v_rcp_f32_e32 v189, v189
	v_rcp_f32_e32 v190, v190
	v_rcp_f32_e32 v191, v191
	v_rcp_f32_e32 v192, v192
	v_rcp_f32_e32 v193, v193
	v_rcp_f32_e32 v194, v194
	v_rcp_f32_e32 v195, v195
	v_rcp_f32_e32 v196, v196
	v_rcp_f32_e32 v197, v197
	v_rcp_f32_e32 v218, v218
	v_rcp_f32_e32 v219, v219
	v_rcp_f32_e32 v220, v220
	v_rcp_f32_e32 v221, v221
	v_rcp_f32_e32 v222, v222
	v_rcp_f32_e32 v223, v223
	v_pk_mul_f32 v[188:189], v[146:147], v[188:189]
	v_pk_mul_f32 v[190:191], v[148:149], v[190:191]
	v_pk_mul_f32 v[192:193], v[150:151], v[192:193]
	v_pk_mul_f32 v[194:195], v[152:153], v[194:195]
	v_pk_mul_f32 v[196:197], v[154:155], v[196:197]
	v_pk_mul_f32 v[218:219], v[156:157], v[218:219]
	v_pk_mul_f32 v[220:221], v[158:159], v[220:221]
	v_pk_mul_f32 v[222:223], v[160:161], v[222:223]
	v_pk_mul_f32 v[188:189], v[188:189], v[130:131]
	v_pk_mul_f32 v[190:191], v[190:191], v[132:133]
	v_pk_mul_f32 v[192:193], v[192:193], v[134:135]
	v_pk_mul_f32 v[194:195], v[194:195], v[136:137]
	v_pk_mul_f32 v[196:197], v[196:197], v[138:139]
	v_pk_mul_f32 v[218:219], v[218:219], v[140:141]
	v_pk_mul_f32 v[220:221], v[220:221], v[142:143]
	v_pk_mul_f32 v[222:223], v[222:223], v[144:145]
	v_cvt_pk_bf16_f32 v188, v188, v189
	v_cvt_pk_bf16_f32 v190, v190, v191
	v_cvt_pk_bf16_f32 v192, v192, v193
	v_cvt_pk_bf16_f32 v194, v194, v195
	v_cvt_pk_bf16_f32 v196, v196, v197
	v_cvt_pk_bf16_f32 v218, v218, v219
	v_cvt_pk_bf16_f32 v220, v220, v221
	v_cvt_pk_bf16_f32 v222, v222, v223
	ds_write_b16 v224, v188 offset:0
	ds_write_b16_d16_hi v237, v188 offset:64
	ds_write_b16 v224, v190 offset:128
	ds_write_b16_d16_hi v237, v190 offset:192
	ds_write_b16 v224, v192 offset:512
	ds_write_b16_d16_hi v237, v192 offset:576
	ds_write_b16 v224, v194 offset:640
	ds_write_b16_d16_hi v237, v194 offset:704
	ds_write_b16 v224, v196 offset:1024
	ds_write_b16_d16_hi v237, v196 offset:1088
	ds_write_b16 v224, v218 offset:1152
	ds_write_b16_d16_hi v237, v218 offset:1216
	ds_write_b16 v224, v220 offset:1536
	ds_write_b16_d16_hi v237, v220 offset:1600
	ds_write_b16 v224, v222 offset:1664
; DI unsigned pack2(float a, float b) { f2 v = {a, b}; bf2 r = __builtin_convertvector(v, bf2); return __builtin_bit_cast(unsigned, r); }
; DI float ex2(float x) { return __builtin_amdgcn_exp2f(x); }
; DI float gelu_tanh(float g) {
;   const float u = g * g;
;   const float t = g * (-2.302208198f - 0.1029432397f * u);
;   const float e = ex2(t);
;   return g * __builtin_amdgcn_rcpf(1.f + e);
; }
;   DI void operator()(f32x16 (&acc)[2][4], int wm, int wn, int r, int h) {
;     ...
;             float prev0 = __int_as_float(pv << 16), prev1 = __int_as_float(pv & 0xffff0000);
;             float next0 = __int_as_float(nv << 16), next1 = __int_as_float(nv & 0xffff0000);
;             if (mb == 0 && r == 0) { prev0 = eo0; prev1 = eo1; }
;             if (mb == 3 && r == 31) { next0 = eo0; next1 = eo1; }
;             spm = spc;
;             prev0 *= pm[mb]; prev1 *= pm[mb];
;             next0 *= nm[mb]; next1 *= nm[mb];
;             u[nb][mb][0] = w0[0] * prev0 + w1[0] * acc[nb][mb][i0] + w2[0] * next0 + bz[0];
;             u[nb][mb][1] = w0[1] * prev1 + w1[1] * acc[nb][mb][i0 + 1] + w2[1] * next1 + bz[1];
;           }
;         }
; #pragma unroll
;         for (int mb = 0; mb < 4; ++mb)
;           *(unsigned*)(ost + (mb * 32 + r) * 40 + ig * 8 + h * 4 + qp * 2) =
;               pack2(gelu_tanh(u[1][mb][0]) * u[0][mb][0], gelu_tanh(u[1][mb][1]) * u[0][mb][1]);
	ds_write_b16_d16_hi v237, v222 offset:1728
	v_mov_b32_e32 v186, v18
	v_mov_b32_e32 v187, v66
	v_pk_fma_f32 v[130:131], v[50:51], v[242:243], v[244:245] op_sel_hi:[1,0,0]
	v_pk_fma_f32 v[132:133], v[52:53], v[242:243], v[244:245] op_sel_hi:[1,0,0]
	v_pk_fma_f32 v[134:135], v[54:55], v[242:243], v[244:245] op_sel_hi:[1,0,0]
	v_pk_fma_f32 v[136:137], v[56:57], v[242:243], v[244:245] op_sel_hi:[1,0,0]
	v_pk_fma_f32 v[138:139], v[58:59], v[242:243], v[244:245] op_sel_hi:[1,0,0]
	v_pk_fma_f32 v[140:141], v[60:61], v[242:243], v[244:245] op_sel_hi:[1,0,0]
	v_pk_fma_f32 v[142:143], v[62:63], v[242:243], v[244:245] op_sel_hi:[1,0,0]
	v_pk_fma_f32 v[144:145], v[64:65], v[242:243], v[244:245] op_sel_hi:[1,0,0]
	v_pk_fma_f32 v[146:147], v[82:83], v[250:251], v[252:253] op_sel_hi:[1,0,0]
	v_pk_fma_f32 v[148:149], v[84:85], v[250:251], v[252:253] op_sel_hi:[1,0,0]
	v_pk_fma_f32 v[150:151], v[86:87], v[250:251], v[252:253] op_sel_hi:[1,0,0]
	v_pk_fma_f32 v[152:153], v[88:89], v[250:251], v[252:253] op_sel_hi:[1,0,0]
	v_pk_fma_f32 v[154:155], v[90:91], v[250:251], v[252:253] op_sel_hi:[1,0,0]
	v_pk_fma_f32 v[156:157], v[92:93], v[250:251], v[252:253] op_sel_hi:[1,0,0]
	v_pk_fma_f32 v[158:159], v[94:95], v[250:251], v[252:253] op_sel_hi:[1,0,0]
	v_pk_fma_f32 v[160:161], v[96:97], v[250:251], v[252:253] op_sel_hi:[1,0,0]
	v_pk_fma_f32 v[130:131], v[50:51], v[240:241], v[130:131] op_sel:[1,0,0] op_sel_hi:[0,1,1]
	v_pk_fma_f32 v[146:147], v[82:83], v[246:247], v[146:147] op_sel:[1,0,0] op_sel_hi:[0,1,1]
	v_pk_fma_f32 v[132:133], v[52:53], v[240:241], v[132:133] op_sel:[1,0,0] op_sel_hi:[0,1,1]
	v_pk_fma_f32 v[148:149], v[84:85], v[246:247], v[148:149] op_sel:[1,0,0] op_sel_hi:[0,1,1]
	v_pk_fma_f32 v[134:135], v[54:55], v[240:241], v[134:135] op_sel:[1,0,0] op_sel_hi:[0,1,1]
	v_pk_fma_f32 v[150:151], v[86:87], v[246:247], v[150:151] op_sel:[1,0,0] op_sel_hi:[0,1,1]
	v_pk_fma_f32 v[136:137], v[56:57], v[240:241], v[136:137] op_sel:[1,0,0] op_sel_hi:[0,1,1]
	v_pk_fma_f32 v[152:153], v[88:89], v[246:247], v[152:153] op_sel:[1,0,0] op_sel_hi:[0,1,1]
	v_pk_fma_f32 v[138:139], v[58:59], v[240:241], v[138:139] op_sel:[1,0,0] op_sel_hi:[0,1,1]
	v_pk_fma_f32 v[154:155], v[90:91], v[246:247], v[154:155] op_sel:[1,0,0] op_sel_hi:[0,1,1]
	v_pk_fma_f32 v[140:141], v[60:61], v[240:241], v[140:141] op_sel:[1,0,0] op_sel_hi:[0,1,1]
	v_pk_fma_f32 v[156:157], v[92:93], v[246:247], v[156:157] op_sel:[1,0,0] op_sel_hi:[0,1,1]
	v_pk_fma_f32 v[142:143], v[62:63], v[240:241], v[142:143] op_sel:[1,0,0] op_sel_hi:[0,1,1]
	v_pk_fma_f32 v[158:159], v[94:95], v[246:247], v[158:159] op_sel:[1,0,0] op_sel_hi:[0,1,1]
	v_pk_fma_f32 v[144:145], v[64:65], v[240:241], v[144:145] op_sel:[1,0,0] op_sel_hi:[0,1,1]
	v_pk_fma_f32 v[160:161], v[96:97], v[246:247], v[160:161] op_sel:[1,0,0] op_sel_hi:[0,1,1]
	v_permlane32_swap_b32_e32 v50, v53
	v_permlane32_swap_b32_e32 v54, v57
	v_permlane32_swap_b32_e32 v58, v61
	v_permlane32_swap_b32_e32 v62, v65
	v_permlane32_swap_b32_e32 v82, v85
	v_permlane32_swap_b32_e32 v86, v89
	v_permlane32_swap_b32_e32 v90, v93
	v_permlane32_swap_b32_e32 v94, v97
	v_permlane32_swap_b32_e32 v53, v54
	v_permlane32_swap_b32_e32 v57, v58
	v_permlane32_swap_b32_e32 v61, v62
	v_permlane32_swap_b32_e32 v85, v86
	v_permlane32_swap_b32_e32 v89, v90
	v_permlane32_swap_b32_e32 v93, v94
	v_permlane32_swap_b32_e32 v65, v186
	v_permlane32_swap_b32_e32 v97, v187
	s_mov_b32 exec_hi, 0
	v_mov_b32_e32 v50, v184
	v_mov_b32_e32 v82, v185
	s_mov_b64 exec, -1
	v_fmac_f32_e32 v131, v240, v52
	v_fmac_f32_e32 v132, v241, v51
	v_fmac_f32_e32 v135, v240, v56
	v_fmac_f32_e32 v136, v241, v55
	v_fmac_f32_e32 v139, v240, v60
	v_fmac_f32_e32 v140, v241, v59
	v_fmac_f32_e32 v143, v240, v64
	v_fmac_f32_e32 v144, v241, v63
	v_fmac_f32_e32 v147, v246, v84
	v_fmac_f32_e32 v148, v247, v83
	v_fmac_f32_e32 v151, v246, v88
	v_fmac_f32_e32 v152, v247, v87
	v_fmac_f32_e32 v155, v246, v92
	v_fmac_f32_e32 v156, v247, v91
	v_fmac_f32_e32 v159, v246, v96
	v_fmac_f32_e32 v160, v247, v95
	v_fmac_f32_e32 v130, v241, v50
	v_fmac_f32_e32 v133, v240, v53
	v_fmac_f32_e32 v134, v241, v54
	v_fmac_f32_e32 v137, v240, v57
	v_fmac_f32_e32 v138, v241, v58
	v_fmac_f32_e32 v141, v240, v61
	v_fmac_f32_e32 v142, v241, v62
	v_fmac_f32_e32 v145, v240, v65
	v_fmac_f32_e32 v146, v247, v82
	v_fmac_f32_e32 v149, v246, v85
	v_fmac_f32_e32 v150, v247, v86
	v_fmac_f32_e32 v153, v246, v89
	v_fmac_f32_e32 v154, v247, v90
	v_fmac_f32_e32 v157, v246, v93
	v_fmac_f32_e32 v158, v247, v94
	v_fmac_f32_e32 v161, v246, v97
	v_pk_mul_f32 v[188:189], v[146:147], v[146:147]
	v_pk_mul_f32 v[190:191], v[148:149], v[148:149]
	v_pk_mul_f32 v[192:193], v[150:151], v[150:151]
	v_pk_mul_f32 v[194:195], v[152:153], v[152:153]
	v_pk_mul_f32 v[196:197], v[154:155], v[154:155]
	v_pk_mul_f32 v[218:219], v[156:157], v[156:157]
	v_pk_mul_f32 v[220:221], v[158:159], v[158:159]
	v_pk_mul_f32 v[222:223], v[160:161], v[160:161]
	v_pk_fma_f32 v[188:189], v[188:189], v[178:179], v[180:181] op_sel_hi:[1,0,0]
	v_pk_fma_f32 v[190:191], v[190:191], v[178:179], v[180:181] op_sel_hi:[1,0,0]
	v_pk_fma_f32 v[192:193], v[192:193], v[178:179], v[180:181] op_sel_hi:[1,0,0]
	v_pk_fma_f32 v[194:195], v[194:195], v[178:179], v[180:181] op_sel_hi:[1,0,0]
	v_pk_fma_f32 v[196:197], v[196:197], v[178:179], v[180:181] op_sel_hi:[1,0,0]
	v_pk_fma_f32 v[218:219], v[218:219], v[178:179], v[180:181] op_sel_hi:[1,0,0]
	v_pk_fma_f32 v[220:221], v[220:221], v[178:179], v[180:181] op_sel_hi:[1,0,0]
	v_pk_fma_f32 v[222:223], v[222:223], v[178:179], v[180:181] op_sel_hi:[1,0,0]
	v_pk_mul_f32 v[188:189], v[146:147], v[188:189]
	v_pk_mul_f32 v[190:191], v[148:149], v[190:191]
	v_pk_mul_f32 v[192:193], v[150:151], v[192:193]
; DI unsigned pack2(float a, float b) { f2 v = {a, b}; bf2 r = __builtin_convertvector(v, bf2); return __builtin_bit_cast(unsigned, r); }
; DI float ex2(float x) { return __builtin_amdgcn_exp2f(x); }
; DI float gelu_tanh(float g) {
;   const float u = g * g;
;   const float t = g * (-2.302208198f - 0.1029432397f * u);
;   const float e = ex2(t);
;   return g * __builtin_amdgcn_rcpf(1.f + e);
; }
;   DI void operator()(f32x16 (&acc)[2][4], int wm, int wn, int r, int h) {
;     ...
;             u[nb][mb][0] = w0[0] * prev0 + w1[0] * acc[nb][mb][i0] + w2[0] * next0 + bz[0];
;             u[nb][mb][1] = w0[1] * prev1 + w1[1] * acc[nb][mb][i0 + 1] + w2[1] * next1 + bz[1];
;           }
;         }
; #pragma unroll
;         for (int mb = 0; mb < 4; ++mb)
;           *(unsigned*)(ost + (mb * 32 + r) * 40 + ig * 8 + h * 4 + qp * 2) =
;               pack2(gelu_tanh(u[1][mb][0]) * u[0][mb][0], gelu_tanh(u[1][mb][1]) * u[0][mb][1]);
	v_pk_mul_f32 v[194:195], v[152:153], v[194:195]
	v_pk_mul_f32 v[196:197], v[154:155], v[196:197]
	v_pk_mul_f32 v[218:219], v[156:157], v[218:219]
	v_pk_mul_f32 v[220:221], v[158:159], v[220:221]
	v_pk_mul_f32 v[222:223], v[160:161], v[222:223]
	v_exp_f32_e32 v188, v188
	v_exp_f32_e32 v189, v189
	v_exp_f32_e32 v190, v190
	v_exp_f32_e32 v191, v191
	v_exp_f32_e32 v192, v192
	v_exp_f32_e32 v193, v193
	v_exp_f32_e32 v194, v194
	v_exp_f32_e32 v195, v195
	v_exp_f32_e32 v196, v196
	v_exp_f32_e32 v197, v197
	v_exp_f32_e32 v218, v218
	v_exp_f32_e32 v219, v219
	v_exp_f32_e32 v220, v220
	v_exp_f32_e32 v221, v221
	v_exp_f32_e32 v222, v222
	v_exp_f32_e32 v223, v223
	v_pk_add_f32 v[188:189], v[188:189], v[182:183] op_sel_hi:[1,0]
	v_pk_add_f32 v[190:191], v[190:191], v[182:183] op_sel_hi:[1,0]
	v_pk_add_f32 v[192:193], v[192:193], v[182:183] op_sel_hi:[1,0]
	v_pk_add_f32 v[194:195], v[194:195], v[182:183] op_sel_hi:[1,0]
	v_pk_add_f32 v[196:197], v[196:197], v[182:183] op_sel_hi:[1,0]
	v_pk_add_f32 v[218:219], v[218:219], v[182:183] op_sel_hi:[1,0]
	v_pk_add_f32 v[220:221], v[220:221], v[182:183] op_sel_hi:[1,0]
	v_pk_add_f32 v[222:223], v[222:223], v[182:183] op_sel_hi:[1,0]
	v_rcp_f32_e32 v188, v188
	v_rcp_f32_e32 v189, v189
	v_rcp_f32_e32 v190, v190
	v_rcp_f32_e32 v191, v191
	v_rcp_f32_e32 v192, v192
	v_rcp_f32_e32 v193, v193
	v_rcp_f32_e32 v194, v194
	v_rcp_f32_e32 v195, v195
	v_rcp_f32_e32 v196, v196
	v_rcp_f32_e32 v197, v197
	v_rcp_f32_e32 v218, v218
	v_rcp_f32_e32 v219, v219
	v_rcp_f32_e32 v220, v220
	v_rcp_f32_e32 v221, v221
	v_rcp_f32_e32 v222, v222
	v_rcp_f32_e32 v223, v223
	v_pk_mul_f32 v[188:189], v[146:147], v[188:189]
	v_pk_mul_f32 v[190:191], v[148:149], v[190:191]
	v_pk_mul_f32 v[192:193], v[150:151], v[192:193]
	v_pk_mul_f32 v[194:195], v[152:153], v[194:195]
	v_pk_mul_f32 v[196:197], v[154:155], v[196:197]
	v_pk_mul_f32 v[218:219], v[156:157], v[218:219]
	v_pk_mul_f32 v[220:221], v[158:159], v[220:221]
	v_pk_mul_f32 v[222:223], v[160:161], v[222:223]
	v_pk_mul_f32 v[188:189], v[188:189], v[130:131]
	v_pk_mul_f32 v[190:191], v[190:191], v[132:133]
	v_pk_mul_f32 v[192:193], v[192:193], v[134:135]
	v_pk_mul_f32 v[194:195], v[194:195], v[136:137]
	v_pk_mul_f32 v[196:197], v[196:197], v[138:139]
	v_pk_mul_f32 v[218:219], v[218:219], v[140:141]
	v_pk_mul_f32 v[220:221], v[220:221], v[142:143]
	v_pk_mul_f32 v[222:223], v[222:223], v[144:145]
	v_cvt_pk_bf16_f32 v188, v188, v189
	v_cvt_pk_bf16_f32 v190, v190, v191
	v_cvt_pk_bf16_f32 v192, v192, v193
	v_cvt_pk_bf16_f32 v194, v194, v195
	v_cvt_pk_bf16_f32 v196, v196, v197
	v_cvt_pk_bf16_f32 v218, v218, v219
	v_cvt_pk_bf16_f32 v220, v220, v221
	v_cvt_pk_bf16_f32 v222, v222, v223
	ds_write_b16 v224, v188 offset:2048
	ds_write_b16_d16_hi v237, v188 offset:2112
	ds_write_b16 v224, v190 offset:2176
	ds_write_b16_d16_hi v237, v190 offset:2240
	ds_write_b16 v224, v192 offset:2560
	ds_write_b16_d16_hi v237, v192 offset:2624
	ds_write_b16 v224, v194 offset:2688
	ds_write_b16_d16_hi v237, v194 offset:2752
	ds_write_b16 v224, v196 offset:3072
	ds_write_b16_d16_hi v237, v196 offset:3136
	ds_write_b16 v224, v218 offset:3200
	ds_write_b16_d16_hi v237, v218 offset:3264
	ds_write_b16 v224, v220 offset:3584
	ds_write_b16_d16_hi v237, v220 offset:3648
	ds_write_b16 v224, v222 offset:3712
	ds_write_b16_d16_hi v237, v222 offset:3776
	v_mov_b32_e32 v184, v2
	v_mov_b32_e32 v185, v34
	v_pk_fma_f32 v[130:131], v[18:19], v[242:243], v[244:245] op_sel_hi:[1,0,0]
	v_pk_fma_f32 v[132:133], v[20:21], v[242:243], v[244:245] op_sel_hi:[1,0,0]
	v_pk_fma_f32 v[134:135], v[22:23], v[242:243], v[244:245] op_sel_hi:[1,0,0]
	v_pk_fma_f32 v[136:137], v[24:25], v[242:243], v[244:245] op_sel_hi:[1,0,0]
	v_pk_fma_f32 v[138:139], v[26:27], v[242:243], v[244:245] op_sel_hi:[1,0,0]
	v_pk_fma_f32 v[140:141], v[28:29], v[242:243], v[244:245] op_sel_hi:[1,0,0]
	v_pk_fma_f32 v[142:143], v[30:31], v[242:243], v[244:245] op_sel_hi:[1,0,0]
	v_pk_fma_f32 v[144:145], v[32:33], v[242:243], v[244:245] op_sel_hi:[1,0,0]
	v_pk_fma_f32 v[146:147], v[66:67], v[250:251], v[252:253] op_sel_hi:[1,0,0]
	v_pk_fma_f32 v[148:149], v[68:69], v[250:251], v[252:253] op_sel_hi:[1,0,0]
	v_pk_fma_f32 v[150:151], v[70:71], v[250:251], v[252:253] op_sel_hi:[1,0,0]
	v_pk_fma_f32 v[152:153], v[72:73], v[250:251], v[252:253] op_sel_hi:[1,0,0]
	v_pk_fma_f32 v[154:155], v[74:75], v[250:251], v[252:253] op_sel_hi:[1,0,0]
	v_pk_fma_f32 v[156:157], v[76:77], v[250:251], v[252:253] op_sel_hi:[1,0,0]
	v_pk_fma_f32 v[158:159], v[78:79], v[250:251], v[252:253] op_sel_hi:[1,0,0]
	v_pk_fma_f32 v[160:161], v[80:81], v[250:251], v[252:253] op_sel_hi:[1,0,0]
	v_pk_fma_f32 v[130:131], v[18:19], v[240:241], v[130:131] op_sel:[1,0,0] op_sel_hi:[0,1,1]
	v_pk_fma_f32 v[146:147], v[66:67], v[246:247], v[146:147] op_sel:[1,0,0] op_sel_hi:[0,1,1]
	v_pk_fma_f32 v[132:133], v[20:21], v[240:241], v[132:133] op_sel:[1,0,0] op_sel_hi:[0,1,1]
	v_pk_fma_f32 v[148:149], v[68:69], v[246:247], v[148:149] op_sel:[1,0,0] op_sel_hi:[0,1,1]
	v_pk_fma_f32 v[134:135], v[22:23], v[240:241], v[134:135] op_sel:[1,0,0] op_sel_hi:[0,1,1]
	v_pk_fma_f32 v[150:151], v[70:71], v[246:247], v[150:151] op_sel:[1,0,0] op_sel_hi:[0,1,1]
	v_pk_fma_f32 v[136:137], v[24:25], v[240:241], v[136:137] op_sel:[1,0,0] op_sel_hi:[0,1,1]
	v_pk_fma_f32 v[152:153], v[72:73], v[246:247], v[152:153] op_sel:[1,0,0] op_sel_hi:[0,1,1]
	v_pk_fma_f32 v[138:139], v[26:27], v[240:241], v[138:139] op_sel:[1,0,0] op_sel_hi:[0,1,1]
	v_pk_fma_f32 v[154:155], v[74:75], v[246:247], v[154:155] op_sel:[1,0,0] op_sel_hi:[0,1,1]
	v_pk_fma_f32 v[140:141], v[28:29], v[240:241], v[140:141] op_sel:[1,0,0] op_sel_hi:[0,1,1]
; DI unsigned pack2(float a, float b) { f2 v = {a, b}; bf2 r = __builtin_convertvector(v, bf2); return __builtin_bit_cast(unsigned, r); }
; DI float ex2(float x) { return __builtin_amdgcn_exp2f(x); }
; DI float gelu_tanh(float g) {
;   const float u = g * g;
;   const float t = g * (-2.302208198f - 0.1029432397f * u);
;   const float e = ex2(t);
;   return g * __builtin_amdgcn_rcpf(1.f + e);
; }
;   DI void operator()(f32x16 (&acc)[2][4], int wm, int wn, int r, int h) {
;     ...
;             float prev0 = __int_as_float(pv << 16), prev1 = __int_as_float(pv & 0xffff0000);
;             float next0 = __int_as_float(nv << 16), next1 = __int_as_float(nv & 0xffff0000);
;             if (mb == 0 && r == 0) { prev0 = eo0; prev1 = eo1; }
;             if (mb == 3 && r == 31) { next0 = eo0; next1 = eo1; }
;             spm = spc;
;             prev0 *= pm[mb]; prev1 *= pm[mb];
;             next0 *= nm[mb]; next1 *= nm[mb];
;             u[nb][mb][0] = w0[0] * prev0 + w1[0] * acc[nb][mb][i0] + w2[0] * next0 + bz[0];
;             u[nb][mb][1] = w0[1] * prev1 + w1[1] * acc[nb][mb][i0 + 1] + w2[1] * next1 + bz[1];
;           }
;         }
; #pragma unroll
;         for (int mb = 0; mb < 4; ++mb)
;           *(unsigned*)(ost + (mb * 32 + r) * 40 + ig * 8 + h * 4 + qp * 2) =
;               pack2(gelu_tanh(u[1][mb][0]) * u[0][mb][0], gelu_tanh(u[1][mb][1]) * u[0][mb][1]);
	v_pk_fma_f32 v[156:157], v[76:77], v[246:247], v[156:157] op_sel:[1,0,0] op_sel_hi:[0,1,1]
	v_pk_fma_f32 v[142:143], v[30:31], v[240:241], v[142:143] op_sel:[1,0,0] op_sel_hi:[0,1,1]
	v_pk_fma_f32 v[158:159], v[78:79], v[246:247], v[158:159] op_sel:[1,0,0] op_sel_hi:[0,1,1]
	v_pk_fma_f32 v[144:145], v[32:33], v[240:241], v[144:145] op_sel:[1,0,0] op_sel_hi:[0,1,1]
	v_pk_fma_f32 v[160:161], v[80:81], v[246:247], v[160:161] op_sel:[1,0,0] op_sel_hi:[0,1,1]
	v_permlane32_swap_b32_e32 v18, v21
	v_permlane32_swap_b32_e32 v22, v25
	v_permlane32_swap_b32_e32 v26, v29
	v_permlane32_swap_b32_e32 v30, v33
	v_permlane32_swap_b32_e32 v66, v69
	v_permlane32_swap_b32_e32 v70, v73
	v_permlane32_swap_b32_e32 v74, v77
	v_permlane32_swap_b32_e32 v78, v81
	v_permlane32_swap_b32_e32 v21, v22
	v_permlane32_swap_b32_e32 v25, v26
	v_permlane32_swap_b32_e32 v29, v30
	v_permlane32_swap_b32_e32 v69, v70
	v_permlane32_swap_b32_e32 v73, v74
	v_permlane32_swap_b32_e32 v77, v78
	v_permlane32_swap_b32_e32 v33, v184
	v_permlane32_swap_b32_e32 v81, v185
	s_mov_b32 exec_hi, 0
	v_mov_b32_e32 v18, v186
	v_mov_b32_e32 v66, v187
	s_mov_b64 exec, -1
	v_fmac_f32_e32 v131, v240, v20
	v_fmac_f32_e32 v132, v241, v19
	v_fmac_f32_e32 v135, v240, v24
	v_fmac_f32_e32 v136, v241, v23
	v_fmac_f32_e32 v139, v240, v28
	v_fmac_f32_e32 v140, v241, v27
	v_fmac_f32_e32 v143, v240, v32
	v_fmac_f32_e32 v144, v241, v31
	v_fmac_f32_e32 v147, v246, v68
	v_fmac_f32_e32 v148, v247, v67
	v_fmac_f32_e32 v151, v246, v72
	v_fmac_f32_e32 v152, v247, v71
	v_fmac_f32_e32 v155, v246, v76
	v_fmac_f32_e32 v156, v247, v75
	v_fmac_f32_e32 v159, v246, v80
	v_fmac_f32_e32 v160, v247, v79
	v_fmac_f32_e32 v130, v241, v18
	v_fmac_f32_e32 v133, v240, v21
	v_fmac_f32_e32 v134, v241, v22
	v_fmac_f32_e32 v137, v240, v25
	v_fmac_f32_e32 v138, v241, v26
	v_fmac_f32_e32 v141, v240, v29
	v_fmac_f32_e32 v142, v241, v30
	v_fmac_f32_e32 v145, v240, v33
	v_fmac_f32_e32 v146, v247, v66
	v_fmac_f32_e32 v149, v246, v69
	v_fmac_f32_e32 v150, v247, v70
	v_fmac_f32_e32 v153, v246, v73
	v_fmac_f32_e32 v154, v247, v74
	v_fmac_f32_e32 v157, v246, v77
	v_fmac_f32_e32 v158, v247, v78
	v_fmac_f32_e32 v161, v246, v81
	v_pk_mul_f32 v[188:189], v[146:147], v[146:147]
	v_pk_mul_f32 v[190:191], v[148:149], v[148:149]
	v_pk_mul_f32 v[192:193], v[150:151], v[150:151]
	v_pk_mul_f32 v[194:195], v[152:153], v[152:153]
	v_pk_mul_f32 v[196:197], v[154:155], v[154:155]
	v_pk_mul_f32 v[218:219], v[156:157], v[156:157]
	v_pk_mul_f32 v[220:221], v[158:159], v[158:159]
	v_pk_mul_f32 v[222:223], v[160:161], v[160:161]
	v_pk_fma_f32 v[188:189], v[188:189], v[178:179], v[180:181] op_sel_hi:[1,0,0]
	v_pk_fma_f32 v[190:191], v[190:191], v[178:179], v[180:181] op_sel_hi:[1,0,0]
	v_pk_fma_f32 v[192:193], v[192:193], v[178:179], v[180:181] op_sel_hi:[1,0,0]
	v_pk_fma_f32 v[194:195], v[194:195], v[178:179], v[180:181] op_sel_hi:[1,0,0]
	v_pk_fma_f32 v[196:197], v[196:197], v[178:179], v[180:181] op_sel_hi:[1,0,0]
	v_pk_fma_f32 v[218:219], v[218:219], v[178:179], v[180:181] op_sel_hi:[1,0,0]
	v_pk_fma_f32 v[220:221], v[220:221], v[178:179], v[180:181] op_sel_hi:[1,0,0]
	v_pk_fma_f32 v[222:223], v[222:223], v[178:179], v[180:181] op_sel_hi:[1,0,0]
	v_pk_mul_f32 v[188:189], v[146:147], v[188:189]
	v_pk_mul_f32 v[190:191], v[148:149], v[190:191]
	v_pk_mul_f32 v[192:193], v[150:151], v[192:193]
	v_pk_mul_f32 v[194:195], v[152:153], v[194:195]
	v_pk_mul_f32 v[196:197], v[154:155], v[196:197]
	v_pk_mul_f32 v[218:219], v[156:157], v[218:219]
	v_pk_mul_f32 v[220:221], v[158:159], v[220:221]
	v_pk_mul_f32 v[222:223], v[160:161], v[222:223]
	v_exp_f32_e32 v188, v188
	v_exp_f32_e32 v189, v189
	v_exp_f32_e32 v190, v190
	v_exp_f32_e32 v191, v191
	v_exp_f32_e32 v192, v192
	v_exp_f32_e32 v193, v193
	v_exp_f32_e32 v194, v194
	v_exp_f32_e32 v195, v195
	v_exp_f32_e32 v196, v196
	v_exp_f32_e32 v197, v197
	v_exp_f32_e32 v218, v218
	v_exp_f32_e32 v219, v219
	v_exp_f32_e32 v220, v220
	v_exp_f32_e32 v221, v221
	v_exp_f32_e32 v222, v222
	v_exp_f32_e32 v223, v223
	v_pk_add_f32 v[188:189], v[188:189], v[182:183] op_sel_hi:[1,0]
	v_pk_add_f32 v[190:191], v[190:191], v[182:183] op_sel_hi:[1,0]
	v_pk_add_f32 v[192:193], v[192:193], v[182:183] op_sel_hi:[1,0]
	v_pk_add_f32 v[194:195], v[194:195], v[182:183] op_sel_hi:[1,0]
	v_pk_add_f32 v[196:197], v[196:197], v[182:183] op_sel_hi:[1,0]
	v_pk_add_f32 v[218:219], v[218:219], v[182:183] op_sel_hi:[1,0]
	v_pk_add_f32 v[220:221], v[220:221], v[182:183] op_sel_hi:[1,0]
	v_pk_add_f32 v[222:223], v[222:223], v[182:183] op_sel_hi:[1,0]
	v_rcp_f32_e32 v188, v188
	v_rcp_f32_e32 v189, v189
	v_rcp_f32_e32 v190, v190
	v_rcp_f32_e32 v191, v191
	v_rcp_f32_e32 v192, v192
	v_rcp_f32_e32 v193, v193
	v_rcp_f32_e32 v194, v194
	v_rcp_f32_e32 v195, v195
	v_rcp_f32_e32 v196, v196
	v_rcp_f32_e32 v197, v197
	v_rcp_f32_e32 v218, v218
	v_rcp_f32_e32 v219, v219
	v_rcp_f32_e32 v220, v220
	v_rcp_f32_e32 v221, v221
	v_rcp_f32_e32 v222, v222
	v_rcp_f32_e32 v223, v223
	v_pk_mul_f32 v[188:189], v[146:147], v[188:189]
	v_pk_mul_f32 v[190:191], v[148:149], v[190:191]
	v_pk_mul_f32 v[192:193], v[150:151], v[192:193]
	v_pk_mul_f32 v[194:195], v[152:153], v[194:195]
	v_pk_mul_f32 v[196:197], v[154:155], v[196:197]
	v_pk_mul_f32 v[218:219], v[156:157], v[218:219]
	v_pk_mul_f32 v[220:221], v[158:159], v[220:221]
	v_pk_mul_f32 v[222:223], v[160:161], v[222:223]
	v_pk_mul_f32 v[188:189], v[188:189], v[130:131]
	v_pk_mul_f32 v[190:191], v[190:191], v[132:133]
	v_pk_mul_f32 v[192:193], v[192:193], v[134:135]
	v_pk_mul_f32 v[194:195], v[194:195], v[136:137]
	v_pk_mul_f32 v[196:197], v[196:197], v[138:139]
	v_pk_mul_f32 v[218:219], v[218:219], v[140:141]
	v_pk_mul_f32 v[220:221], v[220:221], v[142:143]
; DI unsigned pack2(float a, float b) { f2 v = {a, b}; bf2 r = __builtin_convertvector(v, bf2); return __builtin_bit_cast(unsigned, r); }
;   DI void operator()(f32x16 (&acc)[2][4], int wm, int wn, int r, int h) {
;     ...
;             float prev0 = __int_as_float(pv << 16), prev1 = __int_as_float(pv & 0xffff0000);
;             float next0 = __int_as_float(nv << 16), next1 = __int_as_float(nv & 0xffff0000);
;             if (mb == 0 && r == 0) { prev0 = eo0; prev1 = eo1; }
;             if (mb == 3 && r == 31) { next0 = eo0; next1 = eo1; }
;             spm = spc;
;             prev0 *= pm[mb]; prev1 *= pm[mb];
;             next0 *= nm[mb]; next1 *= nm[mb];
;             u[nb][mb][0] = w0[0] * prev0 + w1[0] * acc[nb][mb][i0] + w2[0] * next0 + bz[0];
;             u[nb][mb][1] = w0[1] * prev1 + w1[1] * acc[nb][mb][i0 + 1] + w2[1] * next1 + bz[1];
;           }
;         }
; #pragma unroll
;         for (int mb = 0; mb < 4; ++mb)
;           *(unsigned*)(ost + (mb * 32 + r) * 40 + ig * 8 + h * 4 + qp * 2) =
;               pack2(gelu_tanh(u[1][mb][0]) * u[0][mb][0], gelu_tanh(u[1][mb][1]) * u[0][mb][1]);
	v_pk_mul_f32 v[222:223], v[222:223], v[144:145]
	v_cvt_pk_bf16_f32 v188, v188, v189
	v_cvt_pk_bf16_f32 v190, v190, v191
	v_cvt_pk_bf16_f32 v192, v192, v193
	v_cvt_pk_bf16_f32 v194, v194, v195
	v_cvt_pk_bf16_f32 v196, v196, v197
	v_cvt_pk_bf16_f32 v218, v218, v219
	v_cvt_pk_bf16_f32 v220, v220, v221
	v_cvt_pk_bf16_f32 v222, v222, v223
	ds_write_b16 v224, v188 offset:4096
	ds_write_b16_d16_hi v237, v188 offset:4160
	ds_write_b16 v224, v190 offset:4224
	ds_write_b16_d16_hi v237, v190 offset:4288
	ds_write_b16 v224, v192 offset:4608
	ds_write_b16_d16_hi v237, v192 offset:4672
	ds_write_b16 v224, v194 offset:4736
	ds_write_b16_d16_hi v237, v194 offset:4800
	ds_write_b16 v224, v196 offset:5120
	ds_write_b16_d16_hi v237, v196 offset:5184
	ds_write_b16 v224, v218 offset:5248
	ds_write_b16_d16_hi v237, v218 offset:5312
	ds_write_b16 v224, v220 offset:5632
	ds_write_b16_d16_hi v237, v220 offset:5696
	ds_write_b16 v224, v222 offset:5760
	ds_write_b16_d16_hi v237, v222 offset:5824
	v_pk_fma_f32 v[130:131], v[2:3], v[242:243], v[244:245] op_sel_hi:[1,0,0]
	v_pk_fma_f32 v[132:133], v[4:5], v[242:243], v[244:245] op_sel_hi:[1,0,0]
	v_pk_fma_f32 v[134:135], v[6:7], v[242:243], v[244:245] op_sel_hi:[1,0,0]
	v_pk_fma_f32 v[136:137], v[8:9], v[242:243], v[244:245] op_sel_hi:[1,0,0]
	v_pk_fma_f32 v[138:139], v[10:11], v[242:243], v[244:245] op_sel_hi:[1,0,0]
	v_pk_fma_f32 v[140:141], v[12:13], v[242:243], v[244:245] op_sel_hi:[1,0,0]
	v_pk_fma_f32 v[142:143], v[14:15], v[242:243], v[244:245] op_sel_hi:[1,0,0]
	v_pk_fma_f32 v[144:145], v[16:17], v[242:243], v[244:245] op_sel_hi:[1,0,0]
	v_pk_fma_f32 v[146:147], v[34:35], v[250:251], v[252:253] op_sel_hi:[1,0,0]
	v_pk_fma_f32 v[148:149], v[36:37], v[250:251], v[252:253] op_sel_hi:[1,0,0]
	v_pk_fma_f32 v[150:151], v[38:39], v[250:251], v[252:253] op_sel_hi:[1,0,0]
	v_pk_fma_f32 v[152:153], v[40:41], v[250:251], v[252:253] op_sel_hi:[1,0,0]
	v_pk_fma_f32 v[154:155], v[42:43], v[250:251], v[252:253] op_sel_hi:[1,0,0]
	v_pk_fma_f32 v[156:157], v[44:45], v[250:251], v[252:253] op_sel_hi:[1,0,0]
	v_pk_fma_f32 v[158:159], v[46:47], v[250:251], v[252:253] op_sel_hi:[1,0,0]
	v_pk_fma_f32 v[160:161], v[48:49], v[250:251], v[252:253] op_sel_hi:[1,0,0]
	v_pk_fma_f32 v[130:131], v[2:3], v[240:241], v[130:131] op_sel:[1,0,0] op_sel_hi:[0,1,1]
	v_pk_fma_f32 v[146:147], v[34:35], v[246:247], v[146:147] op_sel:[1,0,0] op_sel_hi:[0,1,1]
	v_pk_fma_f32 v[132:133], v[4:5], v[240:241], v[132:133] op_sel:[1,0,0] op_sel_hi:[0,1,1]
	v_pk_fma_f32 v[148:149], v[36:37], v[246:247], v[148:149] op_sel:[1,0,0] op_sel_hi:[0,1,1]
	v_pk_fma_f32 v[134:135], v[6:7], v[240:241], v[134:135] op_sel:[1,0,0] op_sel_hi:[0,1,1]
	v_pk_fma_f32 v[150:151], v[38:39], v[246:247], v[150:151] op_sel:[1,0,0] op_sel_hi:[0,1,1]
	v_pk_fma_f32 v[136:137], v[8:9], v[240:241], v[136:137] op_sel:[1,0,0] op_sel_hi:[0,1,1]
	v_pk_fma_f32 v[152:153], v[40:41], v[246:247], v[152:153] op_sel:[1,0,0] op_sel_hi:[0,1,1]
	v_pk_fma_f32 v[138:139], v[10:11], v[240:241], v[138:139] op_sel:[1,0,0] op_sel_hi:[0,1,1]
	v_pk_fma_f32 v[154:155], v[42:43], v[246:247], v[154:155] op_sel:[1,0,0] op_sel_hi:[0,1,1]
	v_pk_fma_f32 v[140:141], v[12:13], v[240:241], v[140:141] op_sel:[1,0,0] op_sel_hi:[0,1,1]
	v_pk_fma_f32 v[156:157], v[44:45], v[246:247], v[156:157] op_sel:[1,0,0] op_sel_hi:[0,1,1]
	v_pk_fma_f32 v[142:143], v[14:15], v[240:241], v[142:143] op_sel:[1,0,0] op_sel_hi:[0,1,1]
	v_pk_fma_f32 v[158:159], v[46:47], v[246:247], v[158:159] op_sel:[1,0,0] op_sel_hi:[0,1,1]
	v_pk_fma_f32 v[144:145], v[16:17], v[240:241], v[144:145] op_sel:[1,0,0] op_sel_hi:[0,1,1]
	v_pk_fma_f32 v[160:161], v[48:49], v[246:247], v[160:161] op_sel:[1,0,0] op_sel_hi:[0,1,1]
	v_permlane32_swap_b32_e32 v2, v5
	v_permlane32_swap_b32_e32 v6, v9
	v_permlane32_swap_b32_e32 v10, v13
	v_permlane32_swap_b32_e32 v14, v17
	v_permlane32_swap_b32_e32 v34, v37
	v_permlane32_swap_b32_e32 v38, v41
	v_permlane32_swap_b32_e32 v42, v45
	v_permlane32_swap_b32_e32 v46, v49
	v_permlane32_swap_b32_e32 v5, v6
	v_permlane32_swap_b32_e32 v9, v10
	v_permlane32_swap_b32_e32 v13, v14
	v_permlane32_swap_b32_e32 v37, v38
	v_permlane32_swap_b32_e32 v41, v42
	v_permlane32_swap_b32_e32 v45, v46
	s_mov_b32 exec_lo, 0
	ds_read_b32 v17, v226 offset:0
	ds_read_b32 v49, v226 offset:128
	s_mov_b64 exec, -1
	s_mov_b32 exec_hi, 0
	v_mov_b32_e32 v2, v184
	v_mov_b32_e32 v34, v185
	s_mov_b64 exec, -1
	v_fmac_f32_e32 v131, v240, v4
	v_fmac_f32_e32 v132, v241, v3
	v_fmac_f32_e32 v135, v240, v8
	v_fmac_f32_e32 v136, v241, v7
	v_fmac_f32_e32 v139, v240, v12
	v_fmac_f32_e32 v140, v241, v11
	v_fmac_f32_e32 v143, v240, v16
	v_fmac_f32_e32 v144, v241, v15
	v_fmac_f32_e32 v147, v246, v36
	v_fmac_f32_e32 v148, v247, v35
	v_fmac_f32_e32 v151, v246, v40
	v_fmac_f32_e32 v152, v247, v39
	v_fmac_f32_e32 v155, v246, v44
	v_fmac_f32_e32 v156, v247, v43
	v_fmac_f32_e32 v159, v246, v48
	v_fmac_f32_e32 v160, v247, v47
	s_waitcnt lgkmcnt(0)
; DI unsigned pack2(float a, float b) { f2 v = {a, b}; bf2 r = __builtin_convertvector(v, bf2); return __builtin_bit_cast(unsigned, r); }
; DI float ex2(float x) { return __builtin_amdgcn_exp2f(x); }
; DI float gelu_tanh(float g) {
;   const float u = g * g;
;   const float t = g * (-2.302208198f - 0.1029432397f * u);
;   const float e = ex2(t);
;   return g * __builtin_amdgcn_rcpf(1.f + e);
; }
;   DI void operator()(f32x16 (&acc)[2][4], int wm, int wn, int r, int h) {
;     ...
;             float prev0 = __int_as_float(pv << 16), prev1 = __int_as_float(pv & 0xffff0000);
;             float next0 = __int_as_float(nv << 16), next1 = __int_as_float(nv & 0xffff0000);
;             if (mb == 0 && r == 0) { prev0 = eo0; prev1 = eo1; }
;             if (mb == 3 && r == 31) { next0 = eo0; next1 = eo1; }
;             spm = spc;
;             prev0 *= pm[mb]; prev1 *= pm[mb];
;             next0 *= nm[mb]; next1 *= nm[mb];
;             u[nb][mb][0] = w0[0] * prev0 + w1[0] * acc[nb][mb][i0] + w2[0] * next0 + bz[0];
;             u[nb][mb][1] = w0[1] * prev1 + w1[1] * acc[nb][mb][i0 + 1] + w2[1] * next1 + bz[1];
;           }
;         }
; #pragma unroll
;         for (int mb = 0; mb < 4; ++mb)
;           *(unsigned*)(ost + (mb * 32 + r) * 40 + ig * 8 + h * 4 + qp * 2) =
;               pack2(gelu_tanh(u[1][mb][0]) * u[0][mb][0], gelu_tanh(u[1][mb][1]) * u[0][mb][1]);
	v_fmac_f32_e32 v130, v241, v2
	v_fmac_f32_e32 v133, v240, v5
	v_fmac_f32_e32 v134, v241, v6
	v_fmac_f32_e32 v137, v240, v9
	v_fmac_f32_e32 v138, v241, v10
	v_fmac_f32_e32 v141, v240, v13
	v_fmac_f32_e32 v142, v241, v14
	v_fmac_f32_e32 v145, v240, v17
	v_fmac_f32_e32 v146, v247, v34
	v_fmac_f32_e32 v149, v246, v37
	v_fmac_f32_e32 v150, v247, v38
	v_fmac_f32_e32 v153, v246, v41
	v_fmac_f32_e32 v154, v247, v42
	v_fmac_f32_e32 v157, v246, v45
	v_fmac_f32_e32 v158, v247, v46
	v_fmac_f32_e32 v161, v246, v49
	v_pk_mul_f32 v[188:189], v[146:147], v[146:147]
	v_pk_mul_f32 v[190:191], v[148:149], v[148:149]
	v_pk_mul_f32 v[192:193], v[150:151], v[150:151]
	v_pk_mul_f32 v[194:195], v[152:153], v[152:153]
	v_pk_mul_f32 v[196:197], v[154:155], v[154:155]
	v_pk_mul_f32 v[218:219], v[156:157], v[156:157]
	v_pk_mul_f32 v[220:221], v[158:159], v[158:159]
	v_pk_mul_f32 v[222:223], v[160:161], v[160:161]
	v_pk_fma_f32 v[188:189], v[188:189], v[178:179], v[180:181] op_sel_hi:[1,0,0]
	v_pk_fma_f32 v[190:191], v[190:191], v[178:179], v[180:181] op_sel_hi:[1,0,0]
	v_pk_fma_f32 v[192:193], v[192:193], v[178:179], v[180:181] op_sel_hi:[1,0,0]
	v_pk_fma_f32 v[194:195], v[194:195], v[178:179], v[180:181] op_sel_hi:[1,0,0]
	v_pk_fma_f32 v[196:197], v[196:197], v[178:179], v[180:181] op_sel_hi:[1,0,0]
	v_pk_fma_f32 v[218:219], v[218:219], v[178:179], v[180:181] op_sel_hi:[1,0,0]
	v_pk_fma_f32 v[220:221], v[220:221], v[178:179], v[180:181] op_sel_hi:[1,0,0]
	v_pk_fma_f32 v[222:223], v[222:223], v[178:179], v[180:181] op_sel_hi:[1,0,0]
	v_pk_mul_f32 v[188:189], v[146:147], v[188:189]
	v_pk_mul_f32 v[190:191], v[148:149], v[190:191]
	v_pk_mul_f32 v[192:193], v[150:151], v[192:193]
	v_pk_mul_f32 v[194:195], v[152:153], v[194:195]
	v_pk_mul_f32 v[196:197], v[154:155], v[196:197]
	v_pk_mul_f32 v[218:219], v[156:157], v[218:219]
	v_pk_mul_f32 v[220:221], v[158:159], v[220:221]
	v_pk_mul_f32 v[222:223], v[160:161], v[222:223]
	v_exp_f32_e32 v188, v188
	v_exp_f32_e32 v189, v189
	v_exp_f32_e32 v190, v190
	v_exp_f32_e32 v191, v191
	v_exp_f32_e32 v192, v192
	v_exp_f32_e32 v193, v193
	v_exp_f32_e32 v194, v194
	v_exp_f32_e32 v195, v195
	v_exp_f32_e32 v196, v196
	v_exp_f32_e32 v197, v197
	v_exp_f32_e32 v218, v218
	v_exp_f32_e32 v219, v219
	v_exp_f32_e32 v220, v220
	v_exp_f32_e32 v221, v221
	v_exp_f32_e32 v222, v222
	v_exp_f32_e32 v223, v223
	v_pk_add_f32 v[188:189], v[188:189], v[182:183] op_sel_hi:[1,0]
	v_pk_add_f32 v[190:191], v[190:191], v[182:183] op_sel_hi:[1,0]
	v_pk_add_f32 v[192:193], v[192:193], v[182:183] op_sel_hi:[1,0]
	v_pk_add_f32 v[194:195], v[194:195], v[182:183] op_sel_hi:[1,0]
	v_pk_add_f32 v[196:197], v[196:197], v[182:183] op_sel_hi:[1,0]
	v_pk_add_f32 v[218:219], v[218:219], v[182:183] op_sel_hi:[1,0]
	v_pk_add_f32 v[220:221], v[220:221], v[182:183] op_sel_hi:[1,0]
	v_pk_add_f32 v[222:223], v[222:223], v[182:183] op_sel_hi:[1,0]
	v_rcp_f32_e32 v188, v188
	v_rcp_f32_e32 v189, v189
	v_rcp_f32_e32 v190, v190
	v_rcp_f32_e32 v191, v191
	v_rcp_f32_e32 v192, v192
	v_rcp_f32_e32 v193, v193
	v_rcp_f32_e32 v194, v194
	v_rcp_f32_e32 v195, v195
	v_rcp_f32_e32 v196, v196
	v_rcp_f32_e32 v197, v197
	v_rcp_f32_e32 v218, v218
	v_rcp_f32_e32 v219, v219
	v_rcp_f32_e32 v220, v220
	v_rcp_f32_e32 v221, v221
	v_rcp_f32_e32 v222, v222
	v_rcp_f32_e32 v223, v223
	v_pk_mul_f32 v[188:189], v[146:147], v[188:189]
	v_pk_mul_f32 v[190:191], v[148:149], v[190:191]
	v_pk_mul_f32 v[192:193], v[150:151], v[192:193]
	v_pk_mul_f32 v[194:195], v[152:153], v[194:195]
	v_pk_mul_f32 v[196:197], v[154:155], v[196:197]
	v_pk_mul_f32 v[218:219], v[156:157], v[218:219]
	v_pk_mul_f32 v[220:221], v[158:159], v[220:221]
	v_pk_mul_f32 v[222:223], v[160:161], v[222:223]
	v_pk_mul_f32 v[188:189], v[188:189], v[130:131]
	v_pk_mul_f32 v[190:191], v[190:191], v[132:133]
	v_pk_mul_f32 v[192:193], v[192:193], v[134:135]
	v_pk_mul_f32 v[194:195], v[194:195], v[136:137]
	v_pk_mul_f32 v[196:197], v[196:197], v[138:139]
	v_pk_mul_f32 v[218:219], v[218:219], v[140:141]
	v_pk_mul_f32 v[220:221], v[220:221], v[142:143]
	v_pk_mul_f32 v[222:223], v[222:223], v[144:145]
	v_cvt_pk_bf16_f32 v188, v188, v189
	v_cvt_pk_bf16_f32 v190, v190, v191
	v_cvt_pk_bf16_f32 v192, v192, v193
	v_cvt_pk_bf16_f32 v194, v194, v195
	v_cvt_pk_bf16_f32 v196, v196, v197
	v_cvt_pk_bf16_f32 v218, v218, v219
	v_cvt_pk_bf16_f32 v220, v220, v221
	v_cvt_pk_bf16_f32 v222, v222, v223
	ds_write_b16 v224, v188 offset:6144
	ds_write_b16_d16_hi v237, v188 offset:6208
	ds_write_b16 v224, v190 offset:6272
	ds_write_b16_d16_hi v237, v190 offset:6336
	ds_write_b16 v224, v192 offset:6656
	ds_write_b16_d16_hi v237, v192 offset:6720
	ds_write_b16 v224, v194 offset:6784
	ds_write_b16_d16_hi v237, v194 offset:6848
	ds_write_b16 v224, v196 offset:7168
	ds_write_b16_d16_hi v237, v196 offset:7232
	ds_write_b16 v224, v218 offset:7296
	ds_write_b16_d16_hi v237, v218 offset:7360
	ds_write_b16 v224, v220 offset:7680
	ds_write_b16_d16_hi v237, v220 offset:7744
	ds_write_b16 v224, v222 offset:7808
	ds_write_b16_d16_hi v237, v222 offset:7872
	s_branch .Lupe_done
;   DI void operator()(f32x16 (&acc)[2][4], int wm, int wn, int r, int h) {
;     ...
;             const int pv = (mb > 0) ? ((r == 0) ? spm : spc) : spc;
;             const int nv = (mb < 3) ? ((r == 31) ? snn : snc) : snc;
;             float prev0 = __int_as_float(pv << 16), prev1 = __int_as_float(pv & 0xffff0000);
;             float next0 = __int_as_float(nv << 16), next1 = __int_as_float(nv & 0xffff0000);
;             if (mb == 0 && r == 0) { prev0 = eo0; prev1 = eo1; }
;             if (mb == 3 && r == 31) { next0 = eo0; next1 = eo1; }
;             spm = spc;
;             prev0 *= pm[mb]; prev1 *= pm[mb];
;             next0 *= nm[mb]; next1 *= nm[mb];
;             u[nb][mb][0] = w0[0] * prev0 + w1[0] * acc[nb][mb][i0] + w2[0] * next0 + bz[0];
;             u[nb][mb][1] = w0[1] * prev1 + w1[1] * acc[nb][mb][i0 + 1] + w2[1] * next1 + bz[1];
.Lupe_slow:
	v_mov_b32_e32 v184, v50
	v_mov_b32_e32 v185, v82
	v_pk_fma_f32 v[130:131], v[98:99], v[242:243], v[244:245] op_sel_hi:[1,0,0]
	v_pk_fma_f32 v[132:133], v[100:101], v[242:243], v[244:245] op_sel_hi:[1,0,0]
	v_pk_fma_f32 v[134:135], v[102:103], v[242:243], v[244:245] op_sel_hi:[1,0,0]
	v_pk_fma_f32 v[136:137], v[104:105], v[242:243], v[244:245] op_sel_hi:[1,0,0]
	v_pk_fma_f32 v[138:139], v[106:107], v[242:243], v[244:245] op_sel_hi:[1,0,0]
	v_pk_fma_f32 v[140:141], v[108:109], v[242:243], v[244:245] op_sel_hi:[1,0,0]
	v_pk_fma_f32 v[142:143], v[110:111], v[242:243], v[244:245] op_sel_hi:[1,0,0]
	v_pk_fma_f32 v[144:145], v[112:113], v[242:243], v[244:245] op_sel_hi:[1,0,0]
	v_pk_fma_f32 v[146:147], v[114:115], v[250:251], v[252:253] op_sel_hi:[1,0,0]
	v_pk_fma_f32 v[148:149], v[116:117], v[250:251], v[252:253] op_sel_hi:[1,0,0]
	v_pk_fma_f32 v[150:151], v[118:119], v[250:251], v[252:253] op_sel_hi:[1,0,0]
	v_pk_fma_f32 v[152:153], v[120:121], v[250:251], v[252:253] op_sel_hi:[1,0,0]
	v_pk_fma_f32 v[154:155], v[122:123], v[250:251], v[252:253] op_sel_hi:[1,0,0]
	v_pk_fma_f32 v[156:157], v[124:125], v[250:251], v[252:253] op_sel_hi:[1,0,0]
	v_pk_fma_f32 v[158:159], v[126:127], v[250:251], v[252:253] op_sel_hi:[1,0,0]
	v_pk_fma_f32 v[160:161], v[128:129], v[250:251], v[252:253] op_sel_hi:[1,0,0]
	s_cmp_eq_u32 s36, 0
	s_cselect_b64 exec, s[38:39], -1
	v_pk_fma_f32 v[130:131], v[98:99], v[240:241], v[130:131] op_sel:[1,0,0] op_sel_hi:[0,1,1]
	v_pk_fma_f32 v[146:147], v[114:115], v[246:247], v[146:147] op_sel:[1,0,0] op_sel_hi:[0,1,1]
	s_cmp_eq_u32 s36, 1
	s_cselect_b64 exec, s[38:39], -1
	v_pk_fma_f32 v[132:133], v[100:101], v[240:241], v[132:133] op_sel:[1,0,0] op_sel_hi:[0,1,1]
	v_pk_fma_f32 v[148:149], v[116:117], v[246:247], v[148:149] op_sel:[1,0,0] op_sel_hi:[0,1,1]
	s_cmp_eq_u32 s36, 2
	s_cselect_b64 exec, s[38:39], -1
	v_pk_fma_f32 v[134:135], v[102:103], v[240:241], v[134:135] op_sel:[1,0,0] op_sel_hi:[0,1,1]
	v_pk_fma_f32 v[150:151], v[118:119], v[246:247], v[150:151] op_sel:[1,0,0] op_sel_hi:[0,1,1]
	s_cmp_eq_u32 s36, 3
	s_cselect_b64 exec, s[38:39], -1
	v_pk_fma_f32 v[136:137], v[104:105], v[240:241], v[136:137] op_sel:[1,0,0] op_sel_hi:[0,1,1]
	v_pk_fma_f32 v[152:153], v[120:121], v[246:247], v[152:153] op_sel:[1,0,0] op_sel_hi:[0,1,1]
	s_cmp_eq_u32 s36, 4
	s_cselect_b64 exec, s[38:39], -1
	v_pk_fma_f32 v[138:139], v[106:107], v[240:241], v[138:139] op_sel:[1,0,0] op_sel_hi:[0,1,1]
	v_pk_fma_f32 v[154:155], v[122:123], v[246:247], v[154:155] op_sel:[1,0,0] op_sel_hi:[0,1,1]
	s_cmp_eq_u32 s36, 5
	s_cselect_b64 exec, s[38:39], -1
	v_pk_fma_f32 v[140:141], v[108:109], v[240:241], v[140:141] op_sel:[1,0,0] op_sel_hi:[0,1,1]
	v_pk_fma_f32 v[156:157], v[124:125], v[246:247], v[156:157] op_sel:[1,0,0] op_sel_hi:[0,1,1]
	s_cmp_eq_u32 s36, 6
	s_cselect_b64 exec, s[38:39], -1
	v_pk_fma_f32 v[142:143], v[110:111], v[240:241], v[142:143] op_sel:[1,0,0] op_sel_hi:[0,1,1]
	v_pk_fma_f32 v[158:159], v[126:127], v[246:247], v[158:159] op_sel:[1,0,0] op_sel_hi:[0,1,1]
	s_cmp_eq_u32 s36, 7
	s_cselect_b64 exec, s[38:39], -1
	v_pk_fma_f32 v[144:145], v[112:113], v[240:241], v[144:145] op_sel:[1,0,0] op_sel_hi:[0,1,1]
	v_pk_fma_f32 v[160:161], v[128:129], v[246:247], v[160:161] op_sel:[1,0,0] op_sel_hi:[0,1,1]
	s_mov_b64 exec, -1
	s_nop 1
	v_permlane32_swap_b32_e32 v98, v101
	v_permlane32_swap_b32_e32 v102, v105
	v_permlane32_swap_b32_e32 v106, v109
	v_permlane32_swap_b32_e32 v110, v113
	v_permlane32_swap_b32_e32 v114, v117
	v_permlane32_swap_b32_e32 v118, v121
	v_permlane32_swap_b32_e32 v122, v125
	v_permlane32_swap_b32_e32 v126, v129
	v_permlane32_swap_b32_e32 v101, v102
	v_permlane32_swap_b32_e32 v105, v106
	v_permlane32_swap_b32_e32 v109, v110
	v_permlane32_swap_b32_e32 v117, v118
	v_permlane32_swap_b32_e32 v121, v122
	v_permlane32_swap_b32_e32 v125, v126
	v_permlane32_swap_b32_e32 v113, v184
	v_permlane32_swap_b32_e32 v129, v185
	s_waitcnt lgkmcnt(0)
	s_barrier
	s_mov_b32 s101, 0
	s_mov_b32 s2, s9

; DI unsigned pack2(float a, float b) { f2 v = {a, b}; bf2 r = __builtin_convertvector(v, bf2); return __builtin_bit_cast(unsigned, r); }
; DI float ex2(float x) { return __builtin_amdgcn_exp2f(x); }
; DI float gelu_tanh(float g) {
;   const float u = g * g;
;   const float t = g * (-2.302208198f - 0.1029432397f * u);
;   const float e = ex2(t);
;   return g * __builtin_amdgcn_rcpf(1.f + e);
; }
;   DI void operator()(f32x16 (&acc)[2][4], int wm, int wn, int r, int h) {
;     ...
;             float prev0 = __int_as_float(pv << 16), prev1 = __int_as_float(pv & 0xffff0000);
;             float next0 = __int_as_float(nv << 16), next1 = __int_as_float(nv & 0xffff0000);
;             if (mb == 0 && r == 0) { prev0 = eo0; prev1 = eo1; }
;             if (mb == 3 && r == 31) { next0 = eo0; next1 = eo1; }
;             spm = spc;
;             prev0 *= pm[mb]; prev1 *= pm[mb];
;             next0 *= nm[mb]; next1 *= nm[mb];
;             u[nb][mb][0] = w0[0] * prev0 + w1[0] * acc[nb][mb][i0] + w2[0] * next0 + bz[0];
;             u[nb][mb][1] = w0[1] * prev1 + w1[1] * acc[nb][mb][i0 + 1] + w2[1] * next1 + bz[1];
;           }
;         }
; #pragma unroll
;         for (int mb = 0; mb < 4; ++mb)
;           *(unsigned*)(ost + (mb * 32 + r) * 40 + ig * 8 + h * 4 + qp * 2) =
;               pack2(gelu_tanh(u[1][mb][0]) * u[0][mb][0], gelu_tanh(u[1][mb][1]) * u[0][mb][1]);
.Lupf_nones:
	s_mov_b32 exec_hi, 0
	ds_read_b32 v98, v226 offset:256
	ds_read_b32 v114, v226 offset:384
	s_mov_b64 exec, -1
	v_fmac_f32_e32 v131, v240, v100
	v_fmac_f32_e32 v132, v241, v99
	v_fmac_f32_e32 v135, v240, v104
	v_fmac_f32_e32 v136, v241, v103
	v_fmac_f32_e32 v139, v240, v108
	v_fmac_f32_e32 v140, v241, v107
	v_fmac_f32_e32 v143, v240, v112
	v_fmac_f32_e32 v144, v241, v111
	v_fmac_f32_e32 v147, v246, v116
	v_fmac_f32_e32 v148, v247, v115
	v_fmac_f32_e32 v151, v246, v120
	v_fmac_f32_e32 v152, v247, v119
	v_fmac_f32_e32 v155, v246, v124
	v_fmac_f32_e32 v156, v247, v123
	v_fmac_f32_e32 v159, v246, v128
	v_fmac_f32_e32 v160, v247, v127
	s_waitcnt lgkmcnt(0)
	v_fmac_f32_e32 v130, v241, v98
	v_fmac_f32_e32 v133, v240, v101
	v_fmac_f32_e32 v134, v241, v102
	v_fmac_f32_e32 v137, v240, v105
	v_fmac_f32_e32 v138, v241, v106
	v_fmac_f32_e32 v141, v240, v109
	v_fmac_f32_e32 v142, v241, v110
	v_fmac_f32_e32 v145, v240, v113
	v_fmac_f32_e32 v146, v247, v114
	v_fmac_f32_e32 v149, v246, v117
	v_fmac_f32_e32 v150, v247, v118
	v_fmac_f32_e32 v153, v246, v121
	v_fmac_f32_e32 v154, v247, v122
	v_fmac_f32_e32 v157, v246, v125
	v_fmac_f32_e32 v158, v247, v126
	v_fmac_f32_e32 v161, v246, v129
	v_pk_mul_f32 v[188:189], v[146:147], v[146:147]
	v_pk_mul_f32 v[190:191], v[148:149], v[148:149]
	v_pk_mul_f32 v[192:193], v[150:151], v[150:151]
	v_pk_mul_f32 v[194:195], v[152:153], v[152:153]
	v_pk_mul_f32 v[196:197], v[154:155], v[154:155]
	v_pk_mul_f32 v[218:219], v[156:157], v[156:157]
	v_pk_mul_f32 v[220:221], v[158:159], v[158:159]
	v_pk_mul_f32 v[222:223], v[160:161], v[160:161]
	v_pk_fma_f32 v[188:189], v[188:189], v[178:179], v[180:181] op_sel_hi:[1,0,0]
	v_pk_fma_f32 v[190:191], v[190:191], v[178:179], v[180:181] op_sel_hi:[1,0,0]
	v_pk_fma_f32 v[192:193], v[192:193], v[178:179], v[180:181] op_sel_hi:[1,0,0]
	v_pk_fma_f32 v[194:195], v[194:195], v[178:179], v[180:181] op_sel_hi:[1,0,0]
	v_pk_fma_f32 v[196:197], v[196:197], v[178:179], v[180:181] op_sel_hi:[1,0,0]
	v_pk_fma_f32 v[218:219], v[218:219], v[178:179], v[180:181] op_sel_hi:[1,0,0]
	v_pk_fma_f32 v[220:221], v[220:221], v[178:179], v[180:181] op_sel_hi:[1,0,0]
	v_pk_fma_f32 v[222:223], v[222:223], v[178:179], v[180:181] op_sel_hi:[1,0,0]
	v_pk_mul_f32 v[188:189], v[146:147], v[188:189]
	v_pk_mul_f32 v[190:191], v[148:149], v[190:191]
	v_pk_mul_f32 v[192:193], v[150:151], v[192:193]
	v_pk_mul_f32 v[194:195], v[152:153], v[194:195]
	v_pk_mul_f32 v[196:197], v[154:155], v[196:197]
	v_pk_mul_f32 v[218:219], v[156:157], v[218:219]
	v_pk_mul_f32 v[220:221], v[158:159], v[220:221]
	v_pk_mul_f32 v[222:223], v[160:161], v[222:223]
	v_exp_f32_e32 v188, v188
	v_exp_f32_e32 v189, v189
	v_exp_f32_e32 v190, v190
	v_exp_f32_e32 v191, v191
	v_exp_f32_e32 v192, v192
	v_exp_f32_e32 v193, v193
	v_exp_f32_e32 v194, v194
	v_exp_f32_e32 v195, v195
	v_exp_f32_e32 v196, v196
	v_exp_f32_e32 v197, v197
	v_exp_f32_e32 v218, v218
	v_exp_f32_e32 v219, v219
	v_exp_f32_e32 v220, v220
	v_exp_f32_e32 v221, v221
	v_exp_f32_e32 v222, v222
	v_exp_f32_e32 v223, v223
	v_pk_add_f32 v[188:189], v[188:189], v[182:183] op_sel_hi:[1,0]
	v_pk_add_f32 v[190:191], v[190:191], v[182:183] op_sel_hi:[1,0]
	v_pk_add_f32 v[192:193], v[192:193], v[182:183] op_sel_hi:[1,0]
	v_pk_add_f32 v[194:195], v[194:195], v[182:183] op_sel_hi:[1,0]
	v_pk_add_f32 v[196:197], v[196:197], v[182:183] op_sel_hi:[1,0]
	v_pk_add_f32 v[218:219], v[218:219], v[182:183] op_sel_hi:[1,0]
	v_pk_add_f32 v[220:221], v[220:221], v[182:183] op_sel_hi:[1,0]
	v_pk_add_f32 v[222:223], v[222:223], v[182:183] op_sel_hi:[1,0]
	v_rcp_f32_e32 v188, v188
	v_rcp_f32_e32 v189, v189
	v_rcp_f32_e32 v190, v190
	v_rcp_f32_e32 v191, v191
	v_rcp_f32_e32 v192, v192
	v_rcp_f32_e32 v193, v193
	v_rcp_f32_e32 v194, v194
	v_rcp_f32_e32 v195, v195
	v_rcp_f32_e32 v196, v196
	v_rcp_f32_e32 v197, v197
	v_rcp_f32_e32 v218, v218
	v_rcp_f32_e32 v219, v219
	v_rcp_f32_e32 v220, v220
	v_rcp_f32_e32 v221, v221
	v_rcp_f32_e32 v222, v222
	v_rcp_f32_e32 v223, v223
	v_pk_mul_f32 v[188:189], v[146:147], v[188:189]
	v_pk_mul_f32 v[190:191], v[148:149], v[190:191]
	v_pk_mul_f32 v[192:193], v[150:151], v[192:193]
	v_pk_mul_f32 v[194:195], v[152:153], v[194:195]
	v_pk_mul_f32 v[196:197], v[154:155], v[196:197]
	v_pk_mul_f32 v[218:219], v[156:157], v[218:219]
	v_pk_mul_f32 v[220:221], v[158:159], v[220:221]
	v_pk_mul_f32 v[222:223], v[160:161], v[222:223]
	v_pk_mul_f32 v[188:189], v[188:189], v[130:131]
	v_pk_mul_f32 v[190:191], v[190:191], v[132:133]
	v_pk_mul_f32 v[192:193], v[192:193], v[134:135]
	v_pk_mul_f32 v[194:195], v[194:195], v[136:137]
	v_pk_mul_f32 v[196:197], v[196:197], v[138:139]
	v_pk_mul_f32 v[218:219], v[218:219], v[140:141]
	v_pk_mul_f32 v[220:221], v[220:221], v[142:143]
	v_pk_mul_f32 v[222:223], v[222:223], v[144:145]
	v_cvt_pk_bf16_f32 v188, v188, v189
	v_cvt_pk_bf16_f32 v190, v190, v191
	v_cvt_pk_bf16_f32 v192, v192, v193
	v_cvt_pk_bf16_f32 v194, v194, v195
	v_cvt_pk_bf16_f32 v196, v196, v197
	v_cvt_pk_bf16_f32 v218, v218, v219
	v_cvt_pk_bf16_f32 v220, v220, v221
	v_cvt_pk_bf16_f32 v222, v222, v223
	ds_write_b16 v224, v188 offset:0
	ds_write_b16_d16_hi v237, v188 offset:64
	ds_write_b16 v224, v190 offset:128
	ds_write_b16_d16_hi v237, v190 offset:192
	ds_write_b16 v224, v192 offset:512
	ds_write_b16_d16_hi v237, v192 offset:576
	ds_write_b16 v224, v194 offset:640
	ds_write_b16_d16_hi v237, v194 offset:704
	ds_write_b16 v224, v196 offset:1024
	ds_write_b16_d16_hi v237, v196 offset:1088
	ds_write_b16 v224, v218 offset:1152
	ds_write_b16_d16_hi v237, v218 offset:1216
	ds_write_b16 v224, v220 offset:1536
	ds_write_b16_d16_hi v237, v220 offset:1600
	ds_write_b16 v224, v222 offset:1664
; DI unsigned pack2(float a, float b) { f2 v = {a, b}; bf2 r = __builtin_convertvector(v, bf2); return __builtin_bit_cast(unsigned, r); }
;   DI void operator()(f32x16 (&acc)[2][4], int wm, int wn, int r, int h) {
;     ...
;             const int pv = (mb > 0) ? ((r == 0) ? spm : spc) : spc;
;             const int nv = (mb < 3) ? ((r == 31) ? snn : snc) : snc;
;             float prev0 = __int_as_float(pv << 16), prev1 = __int_as_float(pv & 0xffff0000);
;             float next0 = __int_as_float(nv << 16), next1 = __int_as_float(nv & 0xffff0000);
;             if (mb == 0 && r == 0) { prev0 = eo0; prev1 = eo1; }
;             if (mb == 3 && r == 31) { next0 = eo0; next1 = eo1; }
;             spm = spc;
;             prev0 *= pm[mb]; prev1 *= pm[mb];
;             next0 *= nm[mb]; next1 *= nm[mb];
;             u[nb][mb][0] = w0[0] * prev0 + w1[0] * acc[nb][mb][i0] + w2[0] * next0 + bz[0];
;             u[nb][mb][1] = w0[1] * prev1 + w1[1] * acc[nb][mb][i0 + 1] + w2[1] * next1 + bz[1];
;           }
;         }
; #pragma unroll
;         for (int mb = 0; mb < 4; ++mb)
;           *(unsigned*)(ost + (mb * 32 + r) * 40 + ig * 8 + h * 4 + qp * 2) =
;               pack2(gelu_tanh(u[1][mb][0]) * u[0][mb][0], gelu_tanh(u[1][mb][1]) * u[0][mb][1]);
	ds_write_b16_d16_hi v237, v222 offset:1728
	v_mov_b32_e32 v186, v18
	v_mov_b32_e32 v187, v66
	v_pk_fma_f32 v[130:131], v[50:51], v[242:243], v[244:245] op_sel_hi:[1,0,0]
	v_pk_fma_f32 v[132:133], v[52:53], v[242:243], v[244:245] op_sel_hi:[1,0,0]
	v_pk_fma_f32 v[134:135], v[54:55], v[242:243], v[244:245] op_sel_hi:[1,0,0]
	v_pk_fma_f32 v[136:137], v[56:57], v[242:243], v[244:245] op_sel_hi:[1,0,0]
	v_pk_fma_f32 v[138:139], v[58:59], v[242:243], v[244:245] op_sel_hi:[1,0,0]
	v_pk_fma_f32 v[140:141], v[60:61], v[242:243], v[244:245] op_sel_hi:[1,0,0]
	v_pk_fma_f32 v[142:143], v[62:63], v[242:243], v[244:245] op_sel_hi:[1,0,0]
	v_pk_fma_f32 v[144:145], v[64:65], v[242:243], v[244:245] op_sel_hi:[1,0,0]
	v_pk_fma_f32 v[146:147], v[82:83], v[250:251], v[252:253] op_sel_hi:[1,0,0]
	v_pk_fma_f32 v[148:149], v[84:85], v[250:251], v[252:253] op_sel_hi:[1,0,0]
	v_pk_fma_f32 v[150:151], v[86:87], v[250:251], v[252:253] op_sel_hi:[1,0,0]
	v_pk_fma_f32 v[152:153], v[88:89], v[250:251], v[252:253] op_sel_hi:[1,0,0]
	v_pk_fma_f32 v[154:155], v[90:91], v[250:251], v[252:253] op_sel_hi:[1,0,0]
	v_pk_fma_f32 v[156:157], v[92:93], v[250:251], v[252:253] op_sel_hi:[1,0,0]
	v_pk_fma_f32 v[158:159], v[94:95], v[250:251], v[252:253] op_sel_hi:[1,0,0]
	v_pk_fma_f32 v[160:161], v[96:97], v[250:251], v[252:253] op_sel_hi:[1,0,0]
	s_cmp_eq_u32 s36, 8
	s_cselect_b64 exec, s[38:39], -1
	v_pk_fma_f32 v[130:131], v[50:51], v[240:241], v[130:131] op_sel:[1,0,0] op_sel_hi:[0,1,1]
	v_pk_fma_f32 v[146:147], v[82:83], v[246:247], v[146:147] op_sel:[1,0,0] op_sel_hi:[0,1,1]
	s_cmp_eq_u32 s36, 9
	s_cselect_b64 exec, s[38:39], -1
	v_pk_fma_f32 v[132:133], v[52:53], v[240:241], v[132:133] op_sel:[1,0,0] op_sel_hi:[0,1,1]
	v_pk_fma_f32 v[148:149], v[84:85], v[246:247], v[148:149] op_sel:[1,0,0] op_sel_hi:[0,1,1]
	s_cmp_eq_u32 s36, 10
	s_cselect_b64 exec, s[38:39], -1
	v_pk_fma_f32 v[134:135], v[54:55], v[240:241], v[134:135] op_sel:[1,0,0] op_sel_hi:[0,1,1]
	v_pk_fma_f32 v[150:151], v[86:87], v[246:247], v[150:151] op_sel:[1,0,0] op_sel_hi:[0,1,1]
	s_cmp_eq_u32 s36, 11
	s_cselect_b64 exec, s[38:39], -1
	v_pk_fma_f32 v[136:137], v[56:57], v[240:241], v[136:137] op_sel:[1,0,0] op_sel_hi:[0,1,1]
	v_pk_fma_f32 v[152:153], v[88:89], v[246:247], v[152:153] op_sel:[1,0,0] op_sel_hi:[0,1,1]
	s_cmp_eq_u32 s36, 12
	s_cselect_b64 exec, s[38:39], -1
	v_pk_fma_f32 v[138:139], v[58:59], v[240:241], v[138:139] op_sel:[1,0,0] op_sel_hi:[0,1,1]
	v_pk_fma_f32 v[154:155], v[90:91], v[246:247], v[154:155] op_sel:[1,0,0] op_sel_hi:[0,1,1]
	s_cmp_eq_u32 s36, 13
	s_cselect_b64 exec, s[38:39], -1
	v_pk_fma_f32 v[140:141], v[60:61], v[240:241], v[140:141] op_sel:[1,0,0] op_sel_hi:[0,1,1]
	v_pk_fma_f32 v[156:157], v[92:93], v[246:247], v[156:157] op_sel:[1,0,0] op_sel_hi:[0,1,1]
	s_cmp_eq_u32 s36, 14
	s_cselect_b64 exec, s[38:39], -1
	v_pk_fma_f32 v[142:143], v[62:63], v[240:241], v[142:143] op_sel:[1,0,0] op_sel_hi:[0,1,1]
	v_pk_fma_f32 v[158:159], v[94:95], v[246:247], v[158:159] op_sel:[1,0,0] op_sel_hi:[0,1,1]
	s_cmp_eq_u32 s36, 15
	s_cselect_b64 exec, s[38:39], -1
	v_pk_fma_f32 v[144:145], v[64:65], v[240:241], v[144:145] op_sel:[1,0,0] op_sel_hi:[0,1,1]
	v_pk_fma_f32 v[160:161], v[96:97], v[246:247], v[160:161] op_sel:[1,0,0] op_sel_hi:[0,1,1]
	s_mov_b64 exec, -1
	s_nop 1
	v_permlane32_swap_b32_e32 v50, v53
	v_permlane32_swap_b32_e32 v54, v57
	v_permlane32_swap_b32_e32 v58, v61
	v_permlane32_swap_b32_e32 v62, v65
	v_permlane32_swap_b32_e32 v82, v85
	v_permlane32_swap_b32_e32 v86, v89
	v_permlane32_swap_b32_e32 v90, v93
	v_permlane32_swap_b32_e32 v94, v97
	v_permlane32_swap_b32_e32 v53, v54
	v_permlane32_swap_b32_e32 v57, v58
	v_permlane32_swap_b32_e32 v61, v62
	v_permlane32_swap_b32_e32 v85, v86
	v_permlane32_swap_b32_e32 v89, v90
	v_permlane32_swap_b32_e32 v93, v94
	v_permlane32_swap_b32_e32 v65, v186
	v_permlane32_swap_b32_e32 v97, v187
	s_mov_b32 exec_hi, 0
	v_mov_b32_e32 v50, v184
	v_mov_b32_e32 v82, v185
	s_mov_b64 exec, -1
	v_fmac_f32_e32 v131, v240, v52
	v_fmac_f32_e32 v132, v241, v51
	v_fmac_f32_e32 v135, v240, v56
	v_fmac_f32_e32 v136, v241, v55
	v_fmac_f32_e32 v139, v240, v60
	v_fmac_f32_e32 v140, v241, v59
	v_fmac_f32_e32 v143, v240, v64
	v_fmac_f32_e32 v144, v241, v63
	v_fmac_f32_e32 v147, v246, v84
	v_fmac_f32_e32 v148, v247, v83
	v_fmac_f32_e32 v151, v246, v88
	v_fmac_f32_e32 v152, v247, v87
	v_fmac_f32_e32 v155, v246, v92
	v_fmac_f32_e32 v156, v247, v91
	v_fmac_f32_e32 v159, v246, v96
	v_fmac_f32_e32 v160, v247, v95
	v_fmac_f32_e32 v130, v241, v50
	v_fmac_f32_e32 v133, v240, v53
	v_fmac_f32_e32 v134, v241, v54
	v_fmac_f32_e32 v137, v240, v57
	v_fmac_f32_e32 v138, v241, v58
	v_fmac_f32_e32 v141, v240, v61
	v_fmac_f32_e32 v142, v241, v62
	v_fmac_f32_e32 v145, v240, v65
	v_fmac_f32_e32 v146, v247, v82
	v_fmac_f32_e32 v149, v246, v85
	v_fmac_f32_e32 v150, v247, v86
	v_fmac_f32_e32 v153, v246, v89
	v_fmac_f32_e32 v154, v247, v90
	v_fmac_f32_e32 v157, v246, v93
	v_fmac_f32_e32 v158, v247, v94
	v_fmac_f32_e32 v161, v246, v97
	v_pk_mul_f32 v[188:189], v[146:147], v[146:147]
	v_pk_mul_f32 v[190:191], v[148:149], v[148:149]
	v_pk_mul_f32 v[192:193], v[150:151], v[150:151]
	v_pk_mul_f32 v[194:195], v[152:153], v[152:153]
	v_pk_mul_f32 v[196:197], v[154:155], v[154:155]
	v_pk_mul_f32 v[218:219], v[156:157], v[156:157]
	v_pk_mul_f32 v[220:221], v[158:159], v[158:159]
	v_pk_mul_f32 v[222:223], v[160:161], v[160:161]
	v_pk_fma_f32 v[188:189], v[188:189], v[178:179], v[180:181] op_sel_hi:[1,0,0]
	v_pk_fma_f32 v[190:191], v[190:191], v[178:179], v[180:181] op_sel_hi:[1,0,0]
	v_pk_fma_f32 v[192:193], v[192:193], v[178:179], v[180:181] op_sel_hi:[1,0,0]
	v_pk_fma_f32 v[194:195], v[194:195], v[178:179], v[180:181] op_sel_hi:[1,0,0]
; DI unsigned pack2(float a, float b) { f2 v = {a, b}; bf2 r = __builtin_convertvector(v, bf2); return __builtin_bit_cast(unsigned, r); }
; DI float ex2(float x) { return __builtin_amdgcn_exp2f(x); }
; DI float gelu_tanh(float g) {
;   const float u = g * g;
;   const float t = g * (-2.302208198f - 0.1029432397f * u);
;   const float e = ex2(t);
;   return g * __builtin_amdgcn_rcpf(1.f + e);
; }
;   DI void operator()(f32x16 (&acc)[2][4], int wm, int wn, int r, int h) {
;     ...
;             u[nb][mb][0] = w0[0] * prev0 + w1[0] * acc[nb][mb][i0] + w2[0] * next0 + bz[0];
;             u[nb][mb][1] = w0[1] * prev1 + w1[1] * acc[nb][mb][i0 + 1] + w2[1] * next1 + bz[1];
;           }
;         }
; #pragma unroll
;         for (int mb = 0; mb < 4; ++mb)
;           *(unsigned*)(ost + (mb * 32 + r) * 40 + ig * 8 + h * 4 + qp * 2) =
;               pack2(gelu_tanh(u[1][mb][0]) * u[0][mb][0], gelu_tanh(u[1][mb][1]) * u[0][mb][1]);
	v_pk_fma_f32 v[196:197], v[196:197], v[178:179], v[180:181] op_sel_hi:[1,0,0]
	v_pk_fma_f32 v[218:219], v[218:219], v[178:179], v[180:181] op_sel_hi:[1,0,0]
	v_pk_fma_f32 v[220:221], v[220:221], v[178:179], v[180:181] op_sel_hi:[1,0,0]
	v_pk_fma_f32 v[222:223], v[222:223], v[178:179], v[180:181] op_sel_hi:[1,0,0]
	v_pk_mul_f32 v[188:189], v[146:147], v[188:189]
	v_pk_mul_f32 v[190:191], v[148:149], v[190:191]
	v_pk_mul_f32 v[192:193], v[150:151], v[192:193]
	v_pk_mul_f32 v[194:195], v[152:153], v[194:195]
	v_pk_mul_f32 v[196:197], v[154:155], v[196:197]
	v_pk_mul_f32 v[218:219], v[156:157], v[218:219]
	v_pk_mul_f32 v[220:221], v[158:159], v[220:221]
	v_pk_mul_f32 v[222:223], v[160:161], v[222:223]
	v_exp_f32_e32 v188, v188
	v_exp_f32_e32 v189, v189
	v_exp_f32_e32 v190, v190
	v_exp_f32_e32 v191, v191
	v_exp_f32_e32 v192, v192
	v_exp_f32_e32 v193, v193
	v_exp_f32_e32 v194, v194
	v_exp_f32_e32 v195, v195
	v_exp_f32_e32 v196, v196
	v_exp_f32_e32 v197, v197
	v_exp_f32_e32 v218, v218
	v_exp_f32_e32 v219, v219
	v_exp_f32_e32 v220, v220
	v_exp_f32_e32 v221, v221
	v_exp_f32_e32 v222, v222
	v_exp_f32_e32 v223, v223
	v_pk_add_f32 v[188:189], v[188:189], v[182:183] op_sel_hi:[1,0]
	v_pk_add_f32 v[190:191], v[190:191], v[182:183] op_sel_hi:[1,0]
	v_pk_add_f32 v[192:193], v[192:193], v[182:183] op_sel_hi:[1,0]
	v_pk_add_f32 v[194:195], v[194:195], v[182:183] op_sel_hi:[1,0]
	v_pk_add_f32 v[196:197], v[196:197], v[182:183] op_sel_hi:[1,0]
	v_pk_add_f32 v[218:219], v[218:219], v[182:183] op_sel_hi:[1,0]
	v_pk_add_f32 v[220:221], v[220:221], v[182:183] op_sel_hi:[1,0]
	v_pk_add_f32 v[222:223], v[222:223], v[182:183] op_sel_hi:[1,0]
	v_rcp_f32_e32 v188, v188
	v_rcp_f32_e32 v189, v189
	v_rcp_f32_e32 v190, v190
	v_rcp_f32_e32 v191, v191
	v_rcp_f32_e32 v192, v192
	v_rcp_f32_e32 v193, v193
	v_rcp_f32_e32 v194, v194
	v_rcp_f32_e32 v195, v195
	v_rcp_f32_e32 v196, v196
	v_rcp_f32_e32 v197, v197
	v_rcp_f32_e32 v218, v218
	v_rcp_f32_e32 v219, v219
	v_rcp_f32_e32 v220, v220
	v_rcp_f32_e32 v221, v221
	v_rcp_f32_e32 v222, v222
	v_rcp_f32_e32 v223, v223
	v_pk_mul_f32 v[188:189], v[146:147], v[188:189]
	v_pk_mul_f32 v[190:191], v[148:149], v[190:191]
	v_pk_mul_f32 v[192:193], v[150:151], v[192:193]
	v_pk_mul_f32 v[194:195], v[152:153], v[194:195]
	v_pk_mul_f32 v[196:197], v[154:155], v[196:197]
	v_pk_mul_f32 v[218:219], v[156:157], v[218:219]
	v_pk_mul_f32 v[220:221], v[158:159], v[220:221]
	v_pk_mul_f32 v[222:223], v[160:161], v[222:223]
	v_pk_mul_f32 v[188:189], v[188:189], v[130:131]
	v_pk_mul_f32 v[190:191], v[190:191], v[132:133]
	v_pk_mul_f32 v[192:193], v[192:193], v[134:135]
	v_pk_mul_f32 v[194:195], v[194:195], v[136:137]
	v_pk_mul_f32 v[196:197], v[196:197], v[138:139]
	v_pk_mul_f32 v[218:219], v[218:219], v[140:141]
	v_pk_mul_f32 v[220:221], v[220:221], v[142:143]
	v_pk_mul_f32 v[222:223], v[222:223], v[144:145]
	v_cvt_pk_bf16_f32 v188, v188, v189
	v_cvt_pk_bf16_f32 v190, v190, v191
	v_cvt_pk_bf16_f32 v192, v192, v193
	v_cvt_pk_bf16_f32 v194, v194, v195
	v_cvt_pk_bf16_f32 v196, v196, v197
	v_cvt_pk_bf16_f32 v218, v218, v219
	v_cvt_pk_bf16_f32 v220, v220, v221
	v_cvt_pk_bf16_f32 v222, v222, v223
	ds_write_b16 v224, v188 offset:2048
	ds_write_b16_d16_hi v237, v188 offset:2112
	ds_write_b16 v224, v190 offset:2176
	ds_write_b16_d16_hi v237, v190 offset:2240
	ds_write_b16 v224, v192 offset:2560
	ds_write_b16_d16_hi v237, v192 offset:2624
	ds_write_b16 v224, v194 offset:2688
	ds_write_b16_d16_hi v237, v194 offset:2752
	ds_write_b16 v224, v196 offset:3072
	ds_write_b16_d16_hi v237, v196 offset:3136
	ds_write_b16 v224, v218 offset:3200
	ds_write_b16_d16_hi v237, v218 offset:3264
	ds_write_b16 v224, v220 offset:3584
	ds_write_b16_d16_hi v237, v220 offset:3648
	ds_write_b16 v224, v222 offset:3712
	ds_write_b16_d16_hi v237, v222 offset:3776
	v_mov_b32_e32 v184, v2
	v_mov_b32_e32 v185, v34
	v_pk_fma_f32 v[130:131], v[18:19], v[242:243], v[244:245] op_sel_hi:[1,0,0]
	v_pk_fma_f32 v[132:133], v[20:21], v[242:243], v[244:245] op_sel_hi:[1,0,0]
	v_pk_fma_f32 v[134:135], v[22:23], v[242:243], v[244:245] op_sel_hi:[1,0,0]
	v_pk_fma_f32 v[136:137], v[24:25], v[242:243], v[244:245] op_sel_hi:[1,0,0]
	v_pk_fma_f32 v[138:139], v[26:27], v[242:243], v[244:245] op_sel_hi:[1,0,0]
	v_pk_fma_f32 v[140:141], v[28:29], v[242:243], v[244:245] op_sel_hi:[1,0,0]
	v_pk_fma_f32 v[142:143], v[30:31], v[242:243], v[244:245] op_sel_hi:[1,0,0]
	v_pk_fma_f32 v[144:145], v[32:33], v[242:243], v[244:245] op_sel_hi:[1,0,0]
	v_pk_fma_f32 v[146:147], v[66:67], v[250:251], v[252:253] op_sel_hi:[1,0,0]
	v_pk_fma_f32 v[148:149], v[68:69], v[250:251], v[252:253] op_sel_hi:[1,0,0]
	v_pk_fma_f32 v[150:151], v[70:71], v[250:251], v[252:253] op_sel_hi:[1,0,0]
	v_pk_fma_f32 v[152:153], v[72:73], v[250:251], v[252:253] op_sel_hi:[1,0,0]
	v_pk_fma_f32 v[154:155], v[74:75], v[250:251], v[252:253] op_sel_hi:[1,0,0]
	v_pk_fma_f32 v[156:157], v[76:77], v[250:251], v[252:253] op_sel_hi:[1,0,0]
	v_pk_fma_f32 v[158:159], v[78:79], v[250:251], v[252:253] op_sel_hi:[1,0,0]
	v_pk_fma_f32 v[160:161], v[80:81], v[250:251], v[252:253] op_sel_hi:[1,0,0]
	s_cmp_eq_u32 s36, 16
	s_cselect_b64 exec, s[38:39], -1
	v_pk_fma_f32 v[130:131], v[18:19], v[240:241], v[130:131] op_sel:[1,0,0] op_sel_hi:[0,1,1]
	v_pk_fma_f32 v[146:147], v[66:67], v[246:247], v[146:147] op_sel:[1,0,0] op_sel_hi:[0,1,1]
	s_cmp_eq_u32 s36, 17
	s_cselect_b64 exec, s[38:39], -1
	v_pk_fma_f32 v[132:133], v[20:21], v[240:241], v[132:133] op_sel:[1,0,0] op_sel_hi:[0,1,1]
	v_pk_fma_f32 v[148:149], v[68:69], v[246:247], v[148:149] op_sel:[1,0,0] op_sel_hi:[0,1,1]
	s_cmp_eq_u32 s36, 18
	s_cselect_b64 exec, s[38:39], -1
; DI unsigned pack2(float a, float b) { f2 v = {a, b}; bf2 r = __builtin_convertvector(v, bf2); return __builtin_bit_cast(unsigned, r); }
; DI float ex2(float x) { return __builtin_amdgcn_exp2f(x); }
; DI float gelu_tanh(float g) {
;   const float u = g * g;
;   const float t = g * (-2.302208198f - 0.1029432397f * u);
;   const float e = ex2(t);
;   return g * __builtin_amdgcn_rcpf(1.f + e);
; }
;   DI void operator()(f32x16 (&acc)[2][4], int wm, int wn, int r, int h) {
;     ...
;             const int pv = (mb > 0) ? ((r == 0) ? spm : spc) : spc;
;             const int nv = (mb < 3) ? ((r == 31) ? snn : snc) : snc;
;             float prev0 = __int_as_float(pv << 16), prev1 = __int_as_float(pv & 0xffff0000);
;             float next0 = __int_as_float(nv << 16), next1 = __int_as_float(nv & 0xffff0000);
;             if (mb == 0 && r == 0) { prev0 = eo0; prev1 = eo1; }
;             if (mb == 3 && r == 31) { next0 = eo0; next1 = eo1; }
;             spm = spc;
;             prev0 *= pm[mb]; prev1 *= pm[mb];
;             next0 *= nm[mb]; next1 *= nm[mb];
;             u[nb][mb][0] = w0[0] * prev0 + w1[0] * acc[nb][mb][i0] + w2[0] * next0 + bz[0];
;             u[nb][mb][1] = w0[1] * prev1 + w1[1] * acc[nb][mb][i0 + 1] + w2[1] * next1 + bz[1];
;           }
;         }
; #pragma unroll
;         for (int mb = 0; mb < 4; ++mb)
;           *(unsigned*)(ost + (mb * 32 + r) * 40 + ig * 8 + h * 4 + qp * 2) =
;               pack2(gelu_tanh(u[1][mb][0]) * u[0][mb][0], gelu_tanh(u[1][mb][1]) * u[0][mb][1]);
	v_pk_fma_f32 v[134:135], v[22:23], v[240:241], v[134:135] op_sel:[1,0,0] op_sel_hi:[0,1,1]
	v_pk_fma_f32 v[150:151], v[70:71], v[246:247], v[150:151] op_sel:[1,0,0] op_sel_hi:[0,1,1]
	s_cmp_eq_u32 s36, 19
	s_cselect_b64 exec, s[38:39], -1
	v_pk_fma_f32 v[136:137], v[24:25], v[240:241], v[136:137] op_sel:[1,0,0] op_sel_hi:[0,1,1]
	v_pk_fma_f32 v[152:153], v[72:73], v[246:247], v[152:153] op_sel:[1,0,0] op_sel_hi:[0,1,1]
	s_cmp_eq_u32 s36, 20
	s_cselect_b64 exec, s[38:39], -1
	v_pk_fma_f32 v[138:139], v[26:27], v[240:241], v[138:139] op_sel:[1,0,0] op_sel_hi:[0,1,1]
	v_pk_fma_f32 v[154:155], v[74:75], v[246:247], v[154:155] op_sel:[1,0,0] op_sel_hi:[0,1,1]
	s_cmp_eq_u32 s36, 21
	s_cselect_b64 exec, s[38:39], -1
	v_pk_fma_f32 v[140:141], v[28:29], v[240:241], v[140:141] op_sel:[1,0,0] op_sel_hi:[0,1,1]
	v_pk_fma_f32 v[156:157], v[76:77], v[246:247], v[156:157] op_sel:[1,0,0] op_sel_hi:[0,1,1]
	s_cmp_eq_u32 s36, 22
	s_cselect_b64 exec, s[38:39], -1
	v_pk_fma_f32 v[142:143], v[30:31], v[240:241], v[142:143] op_sel:[1,0,0] op_sel_hi:[0,1,1]
	v_pk_fma_f32 v[158:159], v[78:79], v[246:247], v[158:159] op_sel:[1,0,0] op_sel_hi:[0,1,1]
	s_cmp_eq_u32 s36, 23
	s_cselect_b64 exec, s[38:39], -1
	v_pk_fma_f32 v[144:145], v[32:33], v[240:241], v[144:145] op_sel:[1,0,0] op_sel_hi:[0,1,1]
	v_pk_fma_f32 v[160:161], v[80:81], v[246:247], v[160:161] op_sel:[1,0,0] op_sel_hi:[0,1,1]
	s_mov_b64 exec, -1
	s_nop 1
	v_permlane32_swap_b32_e32 v18, v21
	v_permlane32_swap_b32_e32 v22, v25
	v_permlane32_swap_b32_e32 v26, v29
	v_permlane32_swap_b32_e32 v30, v33
	v_permlane32_swap_b32_e32 v66, v69
	v_permlane32_swap_b32_e32 v70, v73
	v_permlane32_swap_b32_e32 v74, v77
	v_permlane32_swap_b32_e32 v78, v81
	v_permlane32_swap_b32_e32 v21, v22
	v_permlane32_swap_b32_e32 v25, v26
	v_permlane32_swap_b32_e32 v29, v30
	v_permlane32_swap_b32_e32 v69, v70
	v_permlane32_swap_b32_e32 v73, v74
	v_permlane32_swap_b32_e32 v77, v78
	v_permlane32_swap_b32_e32 v33, v184
	v_permlane32_swap_b32_e32 v81, v185
	s_mov_b32 exec_hi, 0
	v_mov_b32_e32 v18, v186
	v_mov_b32_e32 v66, v187
	s_mov_b64 exec, -1
	v_fmac_f32_e32 v131, v240, v20
	v_fmac_f32_e32 v132, v241, v19
	v_fmac_f32_e32 v135, v240, v24
	v_fmac_f32_e32 v136, v241, v23
	v_fmac_f32_e32 v139, v240, v28
	v_fmac_f32_e32 v140, v241, v27
	v_fmac_f32_e32 v143, v240, v32
	v_fmac_f32_e32 v144, v241, v31
	v_fmac_f32_e32 v147, v246, v68
	v_fmac_f32_e32 v148, v247, v67
	v_fmac_f32_e32 v151, v246, v72
	v_fmac_f32_e32 v152, v247, v71
	v_fmac_f32_e32 v155, v246, v76
	v_fmac_f32_e32 v156, v247, v75
	v_fmac_f32_e32 v159, v246, v80
	v_fmac_f32_e32 v160, v247, v79
	v_fmac_f32_e32 v130, v241, v18
	v_fmac_f32_e32 v133, v240, v21
	v_fmac_f32_e32 v134, v241, v22
	v_fmac_f32_e32 v137, v240, v25
	v_fmac_f32_e32 v138, v241, v26
	v_fmac_f32_e32 v141, v240, v29
	v_fmac_f32_e32 v142, v241, v30
	v_fmac_f32_e32 v145, v240, v33
	v_fmac_f32_e32 v146, v247, v66
	v_fmac_f32_e32 v149, v246, v69
	v_fmac_f32_e32 v150, v247, v70
	v_fmac_f32_e32 v153, v246, v73
	v_fmac_f32_e32 v154, v247, v74
	v_fmac_f32_e32 v157, v246, v77
	v_fmac_f32_e32 v158, v247, v78
	v_fmac_f32_e32 v161, v246, v81
	v_pk_mul_f32 v[188:189], v[146:147], v[146:147]
	v_pk_mul_f32 v[190:191], v[148:149], v[148:149]
	v_pk_mul_f32 v[192:193], v[150:151], v[150:151]
	v_pk_mul_f32 v[194:195], v[152:153], v[152:153]
	v_pk_mul_f32 v[196:197], v[154:155], v[154:155]
	v_pk_mul_f32 v[218:219], v[156:157], v[156:157]
	v_pk_mul_f32 v[220:221], v[158:159], v[158:159]
	v_pk_mul_f32 v[222:223], v[160:161], v[160:161]
	v_pk_fma_f32 v[188:189], v[188:189], v[178:179], v[180:181] op_sel_hi:[1,0,0]
	v_pk_fma_f32 v[190:191], v[190:191], v[178:179], v[180:181] op_sel_hi:[1,0,0]
	v_pk_fma_f32 v[192:193], v[192:193], v[178:179], v[180:181] op_sel_hi:[1,0,0]
	v_pk_fma_f32 v[194:195], v[194:195], v[178:179], v[180:181] op_sel_hi:[1,0,0]
	v_pk_fma_f32 v[196:197], v[196:197], v[178:179], v[180:181] op_sel_hi:[1,0,0]
	v_pk_fma_f32 v[218:219], v[218:219], v[178:179], v[180:181] op_sel_hi:[1,0,0]
	v_pk_fma_f32 v[220:221], v[220:221], v[178:179], v[180:181] op_sel_hi:[1,0,0]
	v_pk_fma_f32 v[222:223], v[222:223], v[178:179], v[180:181] op_sel_hi:[1,0,0]
	v_pk_mul_f32 v[188:189], v[146:147], v[188:189]
	v_pk_mul_f32 v[190:191], v[148:149], v[190:191]
	v_pk_mul_f32 v[192:193], v[150:151], v[192:193]
	v_pk_mul_f32 v[194:195], v[152:153], v[194:195]
	v_pk_mul_f32 v[196:197], v[154:155], v[196:197]
	v_pk_mul_f32 v[218:219], v[156:157], v[218:219]
	v_pk_mul_f32 v[220:221], v[158:159], v[220:221]
	v_pk_mul_f32 v[222:223], v[160:161], v[222:223]
	v_exp_f32_e32 v188, v188
	v_exp_f32_e32 v189, v189
	v_exp_f32_e32 v190, v190
	v_exp_f32_e32 v191, v191
	v_exp_f32_e32 v192, v192
	v_exp_f32_e32 v193, v193
	v_exp_f32_e32 v194, v194
	v_exp_f32_e32 v195, v195
	v_exp_f32_e32 v196, v196
	v_exp_f32_e32 v197, v197
	v_exp_f32_e32 v218, v218
	v_exp_f32_e32 v219, v219
	v_exp_f32_e32 v220, v220
	v_exp_f32_e32 v221, v221
	v_exp_f32_e32 v222, v222
	v_exp_f32_e32 v223, v223
	v_pk_add_f32 v[188:189], v[188:189], v[182:183] op_sel_hi:[1,0]
	v_pk_add_f32 v[190:191], v[190:191], v[182:183] op_sel_hi:[1,0]
	v_pk_add_f32 v[192:193], v[192:193], v[182:183] op_sel_hi:[1,0]
	v_pk_add_f32 v[194:195], v[194:195], v[182:183] op_sel_hi:[1,0]
	v_pk_add_f32 v[196:197], v[196:197], v[182:183] op_sel_hi:[1,0]
	v_pk_add_f32 v[218:219], v[218:219], v[182:183] op_sel_hi:[1,0]
	v_pk_add_f32 v[220:221], v[220:221], v[182:183] op_sel_hi:[1,0]
	v_pk_add_f32 v[222:223], v[222:223], v[182:183] op_sel_hi:[1,0]
	v_rcp_f32_e32 v188, v188
	v_rcp_f32_e32 v189, v189
	v_rcp_f32_e32 v190, v190
	v_rcp_f32_e32 v191, v191
	v_rcp_f32_e32 v192, v192
	v_rcp_f32_e32 v193, v193
	v_rcp_f32_e32 v194, v194
; DI unsigned pack2(float a, float b) { f2 v = {a, b}; bf2 r = __builtin_convertvector(v, bf2); return __builtin_bit_cast(unsigned, r); }
;   DI void operator()(f32x16 (&acc)[2][4], int wm, int wn, int r, int h) {
;     ...
;             const int pv = (mb > 0) ? ((r == 0) ? spm : spc) : spc;
;             const int nv = (mb < 3) ? ((r == 31) ? snn : snc) : snc;
;             float prev0 = __int_as_float(pv << 16), prev1 = __int_as_float(pv & 0xffff0000);
;             float next0 = __int_as_float(nv << 16), next1 = __int_as_float(nv & 0xffff0000);
;             if (mb == 0 && r == 0) { prev0 = eo0; prev1 = eo1; }
;             if (mb == 3 && r == 31) { next0 = eo0; next1 = eo1; }
;             spm = spc;
;             prev0 *= pm[mb]; prev1 *= pm[mb];
;             next0 *= nm[mb]; next1 *= nm[mb];
;             u[nb][mb][0] = w0[0] * prev0 + w1[0] * acc[nb][mb][i0] + w2[0] * next0 + bz[0];
;             u[nb][mb][1] = w0[1] * prev1 + w1[1] * acc[nb][mb][i0 + 1] + w2[1] * next1 + bz[1];
;           }
;         }
; #pragma unroll
;         for (int mb = 0; mb < 4; ++mb)
;           *(unsigned*)(ost + (mb * 32 + r) * 40 + ig * 8 + h * 4 + qp * 2) =
;               pack2(gelu_tanh(u[1][mb][0]) * u[0][mb][0], gelu_tanh(u[1][mb][1]) * u[0][mb][1]);
	v_rcp_f32_e32 v195, v195
	v_rcp_f32_e32 v196, v196
	v_rcp_f32_e32 v197, v197
	v_rcp_f32_e32 v218, v218
	v_rcp_f32_e32 v219, v219
	v_rcp_f32_e32 v220, v220
	v_rcp_f32_e32 v221, v221
	v_rcp_f32_e32 v222, v222
	v_rcp_f32_e32 v223, v223
	v_pk_mul_f32 v[188:189], v[146:147], v[188:189]
	v_pk_mul_f32 v[190:191], v[148:149], v[190:191]
	v_pk_mul_f32 v[192:193], v[150:151], v[192:193]
	v_pk_mul_f32 v[194:195], v[152:153], v[194:195]
	v_pk_mul_f32 v[196:197], v[154:155], v[196:197]
	v_pk_mul_f32 v[218:219], v[156:157], v[218:219]
	v_pk_mul_f32 v[220:221], v[158:159], v[220:221]
	v_pk_mul_f32 v[222:223], v[160:161], v[222:223]
	v_pk_mul_f32 v[188:189], v[188:189], v[130:131]
	v_pk_mul_f32 v[190:191], v[190:191], v[132:133]
	v_pk_mul_f32 v[192:193], v[192:193], v[134:135]
	v_pk_mul_f32 v[194:195], v[194:195], v[136:137]
	v_pk_mul_f32 v[196:197], v[196:197], v[138:139]
	v_pk_mul_f32 v[218:219], v[218:219], v[140:141]
	v_pk_mul_f32 v[220:221], v[220:221], v[142:143]
	v_pk_mul_f32 v[222:223], v[222:223], v[144:145]
	v_cvt_pk_bf16_f32 v188, v188, v189
	v_cvt_pk_bf16_f32 v190, v190, v191
	v_cvt_pk_bf16_f32 v192, v192, v193
	v_cvt_pk_bf16_f32 v194, v194, v195
	v_cvt_pk_bf16_f32 v196, v196, v197
	v_cvt_pk_bf16_f32 v218, v218, v219
	v_cvt_pk_bf16_f32 v220, v220, v221
	v_cvt_pk_bf16_f32 v222, v222, v223
	ds_write_b16 v224, v188 offset:4096
	ds_write_b16_d16_hi v237, v188 offset:4160
	ds_write_b16 v224, v190 offset:4224
	ds_write_b16_d16_hi v237, v190 offset:4288
	ds_write_b16 v224, v192 offset:4608
	ds_write_b16_d16_hi v237, v192 offset:4672
	ds_write_b16 v224, v194 offset:4736
	ds_write_b16_d16_hi v237, v194 offset:4800
	ds_write_b16 v224, v196 offset:5120
	ds_write_b16_d16_hi v237, v196 offset:5184
	ds_write_b16 v224, v218 offset:5248
	ds_write_b16_d16_hi v237, v218 offset:5312
	ds_write_b16 v224, v220 offset:5632
	ds_write_b16_d16_hi v237, v220 offset:5696
	ds_write_b16 v224, v222 offset:5760
	ds_write_b16_d16_hi v237, v222 offset:5824
	v_pk_fma_f32 v[130:131], v[2:3], v[242:243], v[244:245] op_sel_hi:[1,0,0]
	v_pk_fma_f32 v[132:133], v[4:5], v[242:243], v[244:245] op_sel_hi:[1,0,0]
	v_pk_fma_f32 v[134:135], v[6:7], v[242:243], v[244:245] op_sel_hi:[1,0,0]
	v_pk_fma_f32 v[136:137], v[8:9], v[242:243], v[244:245] op_sel_hi:[1,0,0]
	v_pk_fma_f32 v[138:139], v[10:11], v[242:243], v[244:245] op_sel_hi:[1,0,0]
	v_pk_fma_f32 v[140:141], v[12:13], v[242:243], v[244:245] op_sel_hi:[1,0,0]
	v_pk_fma_f32 v[142:143], v[14:15], v[242:243], v[244:245] op_sel_hi:[1,0,0]
	v_pk_fma_f32 v[144:145], v[16:17], v[242:243], v[244:245] op_sel_hi:[1,0,0]
	v_pk_fma_f32 v[146:147], v[34:35], v[250:251], v[252:253] op_sel_hi:[1,0,0]
	v_pk_fma_f32 v[148:149], v[36:37], v[250:251], v[252:253] op_sel_hi:[1,0,0]
	v_pk_fma_f32 v[150:151], v[38:39], v[250:251], v[252:253] op_sel_hi:[1,0,0]
	v_pk_fma_f32 v[152:153], v[40:41], v[250:251], v[252:253] op_sel_hi:[1,0,0]
	v_pk_fma_f32 v[154:155], v[42:43], v[250:251], v[252:253] op_sel_hi:[1,0,0]
	v_pk_fma_f32 v[156:157], v[44:45], v[250:251], v[252:253] op_sel_hi:[1,0,0]
	v_pk_fma_f32 v[158:159], v[46:47], v[250:251], v[252:253] op_sel_hi:[1,0,0]
	v_pk_fma_f32 v[160:161], v[48:49], v[250:251], v[252:253] op_sel_hi:[1,0,0]
	s_cmp_eq_u32 s36, 24
	s_cselect_b64 exec, s[38:39], -1
	v_pk_fma_f32 v[130:131], v[2:3], v[240:241], v[130:131] op_sel:[1,0,0] op_sel_hi:[0,1,1]
	v_pk_fma_f32 v[146:147], v[34:35], v[246:247], v[146:147] op_sel:[1,0,0] op_sel_hi:[0,1,1]
	s_cmp_eq_u32 s36, 25
	s_cselect_b64 exec, s[38:39], -1
	v_pk_fma_f32 v[132:133], v[4:5], v[240:241], v[132:133] op_sel:[1,0,0] op_sel_hi:[0,1,1]
	v_pk_fma_f32 v[148:149], v[36:37], v[246:247], v[148:149] op_sel:[1,0,0] op_sel_hi:[0,1,1]
	s_cmp_eq_u32 s36, 26
	s_cselect_b64 exec, s[38:39], -1
	v_pk_fma_f32 v[134:135], v[6:7], v[240:241], v[134:135] op_sel:[1,0,0] op_sel_hi:[0,1,1]
	v_pk_fma_f32 v[150:151], v[38:39], v[246:247], v[150:151] op_sel:[1,0,0] op_sel_hi:[0,1,1]
	s_cmp_eq_u32 s36, 27
	s_cselect_b64 exec, s[38:39], -1
	v_pk_fma_f32 v[136:137], v[8:9], v[240:241], v[136:137] op_sel:[1,0,0] op_sel_hi:[0,1,1]
	v_pk_fma_f32 v[152:153], v[40:41], v[246:247], v[152:153] op_sel:[1,0,0] op_sel_hi:[0,1,1]
	s_cmp_eq_u32 s36, 28
	s_cselect_b64 exec, s[38:39], -1
	v_pk_fma_f32 v[138:139], v[10:11], v[240:241], v[138:139] op_sel:[1,0,0] op_sel_hi:[0,1,1]
	v_pk_fma_f32 v[154:155], v[42:43], v[246:247], v[154:155] op_sel:[1,0,0] op_sel_hi:[0,1,1]
	s_cmp_eq_u32 s36, 29
	s_cselect_b64 exec, s[38:39], -1
	v_pk_fma_f32 v[140:141], v[12:13], v[240:241], v[140:141] op_sel:[1,0,0] op_sel_hi:[0,1,1]
	v_pk_fma_f32 v[156:157], v[44:45], v[246:247], v[156:157] op_sel:[1,0,0] op_sel_hi:[0,1,1]
	s_cmp_eq_u32 s36, 30
	s_cselect_b64 exec, s[38:39], -1
	v_pk_fma_f32 v[142:143], v[14:15], v[240:241], v[142:143] op_sel:[1,0,0] op_sel_hi:[0,1,1]
	v_pk_fma_f32 v[158:159], v[46:47], v[246:247], v[158:159] op_sel:[1,0,0] op_sel_hi:[0,1,1]
	s_cmp_eq_u32 s36, 31
	s_cselect_b64 exec, s[38:39], -1
	v_pk_fma_f32 v[144:145], v[16:17], v[240:241], v[144:145] op_sel:[1,0,0] op_sel_hi:[0,1,1]
	v_pk_fma_f32 v[160:161], v[48:49], v[246:247], v[160:161] op_sel:[1,0,0] op_sel_hi:[0,1,1]
	s_mov_b64 exec, -1
	s_nop 1
	v_permlane32_swap_b32_e32 v2, v5
	v_permlane32_swap_b32_e32 v6, v9
	v_permlane32_swap_b32_e32 v10, v13
	v_permlane32_swap_b32_e32 v14, v17
	v_permlane32_swap_b32_e32 v34, v37
	v_permlane32_swap_b32_e32 v38, v41
	v_permlane32_swap_b32_e32 v42, v45
	v_permlane32_swap_b32_e32 v46, v49
	v_permlane32_swap_b32_e32 v5, v6
	v_permlane32_swap_b32_e32 v9, v10
	v_permlane32_swap_b32_e32 v13, v14
	v_permlane32_swap_b32_e32 v37, v38
	v_permlane32_swap_b32_e32 v41, v42
	v_permlane32_swap_b32_e32 v45, v46
	s_mov_b32 exec_lo, 0
	ds_read_b32 v17, v226 offset:0
	ds_read_b32 v49, v226 offset:128
	s_mov_b64 exec, -1
	s_mov_b32 exec_hi, 0
	v_mov_b32_e32 v2, v184
	v_mov_b32_e32 v34, v185
	s_mov_b64 exec, -1
	v_fmac_f32_e32 v131, v240, v4
	v_fmac_f32_e32 v132, v241, v3
	v_fmac_f32_e32 v135, v240, v8
	v_fmac_f32_e32 v136, v241, v7
	v_fmac_f32_e32 v139, v240, v12
	v_fmac_f32_e32 v140, v241, v11
	v_fmac_f32_e32 v143, v240, v16
	v_fmac_f32_e32 v144, v241, v15
	v_fmac_f32_e32 v147, v246, v36
	v_fmac_f32_e32 v148, v247, v35
	v_fmac_f32_e32 v151, v246, v40
	v_fmac_f32_e32 v152, v247, v39
	v_fmac_f32_e32 v155, v246, v44
	v_fmac_f32_e32 v156, v247, v43
	v_fmac_f32_e32 v159, v246, v48
	v_fmac_f32_e32 v160, v247, v47
	s_waitcnt lgkmcnt(0)
; DI unsigned pack2(float a, float b) { f2 v = {a, b}; bf2 r = __builtin_convertvector(v, bf2); return __builtin_bit_cast(unsigned, r); }
; DI float ex2(float x) { return __builtin_amdgcn_exp2f(x); }
; DI float gelu_tanh(float g) {
;   const float u = g * g;
;   const float t = g * (-2.302208198f - 0.1029432397f * u);
;   const float e = ex2(t);
;   return g * __builtin_amdgcn_rcpf(1.f + e);
; }
;   DI void operator()(f32x16 (&acc)[2][4], int wm, int wn, int r, int h) {
;     ...
;             u[nb][mb][0] = w0[0] * prev0 + w1[0] * acc[nb][mb][i0] + w2[0] * next0 + bz[0];
;             u[nb][mb][1] = w0[1] * prev1 + w1[1] * acc[nb][mb][i0 + 1] + w2[1] * next1 + bz[1];
;           }
;         }
; #pragma unroll
;         for (int mb = 0; mb < 4; ++mb)
;           *(unsigned*)(ost + (mb * 32 + r) * 40 + ig * 8 + h * 4 + qp * 2) =
;               pack2(gelu_tanh(u[1][mb][0]) * u[0][mb][0], gelu_tanh(u[1][mb][1]) * u[0][mb][1]);
	v_fmac_f32_e32 v130, v241, v2
	v_fmac_f32_e32 v133, v240, v5
	v_fmac_f32_e32 v134, v241, v6
	v_fmac_f32_e32 v137, v240, v9
	v_fmac_f32_e32 v138, v241, v10
	v_fmac_f32_e32 v141, v240, v13
	v_fmac_f32_e32 v142, v241, v14
	v_fmac_f32_e32 v145, v240, v17
	v_fmac_f32_e32 v146, v247, v34
	v_fmac_f32_e32 v149, v246, v37
	v_fmac_f32_e32 v150, v247, v38
	v_fmac_f32_e32 v153, v246, v41
	v_fmac_f32_e32 v154, v247, v42
	v_fmac_f32_e32 v157, v246, v45
	v_fmac_f32_e32 v158, v247, v46
	v_fmac_f32_e32 v161, v246, v49
	v_pk_mul_f32 v[188:189], v[146:147], v[146:147]
	v_pk_mul_f32 v[190:191], v[148:149], v[148:149]
	v_pk_mul_f32 v[192:193], v[150:151], v[150:151]
	v_pk_mul_f32 v[194:195], v[152:153], v[152:153]
	v_pk_mul_f32 v[196:197], v[154:155], v[154:155]
	v_pk_mul_f32 v[218:219], v[156:157], v[156:157]
	v_pk_mul_f32 v[220:221], v[158:159], v[158:159]
	v_pk_mul_f32 v[222:223], v[160:161], v[160:161]
	v_pk_fma_f32 v[188:189], v[188:189], v[178:179], v[180:181] op_sel_hi:[1,0,0]
	v_pk_fma_f32 v[190:191], v[190:191], v[178:179], v[180:181] op_sel_hi:[1,0,0]
	v_pk_fma_f32 v[192:193], v[192:193], v[178:179], v[180:181] op_sel_hi:[1,0,0]
	v_pk_fma_f32 v[194:195], v[194:195], v[178:179], v[180:181] op_sel_hi:[1,0,0]
	v_pk_fma_f32 v[196:197], v[196:197], v[178:179], v[180:181] op_sel_hi:[1,0,0]
	v_pk_fma_f32 v[218:219], v[218:219], v[178:179], v[180:181] op_sel_hi:[1,0,0]
	v_pk_fma_f32 v[220:221], v[220:221], v[178:179], v[180:181] op_sel_hi:[1,0,0]
	v_pk_fma_f32 v[222:223], v[222:223], v[178:179], v[180:181] op_sel_hi:[1,0,0]
	v_pk_mul_f32 v[188:189], v[146:147], v[188:189]
	v_pk_mul_f32 v[190:191], v[148:149], v[190:191]
	v_pk_mul_f32 v[192:193], v[150:151], v[192:193]
	v_pk_mul_f32 v[194:195], v[152:153], v[194:195]
	v_pk_mul_f32 v[196:197], v[154:155], v[196:197]
	v_pk_mul_f32 v[218:219], v[156:157], v[218:219]
	v_pk_mul_f32 v[220:221], v[158:159], v[220:221]
	v_pk_mul_f32 v[222:223], v[160:161], v[222:223]
	v_exp_f32_e32 v188, v188
	v_exp_f32_e32 v189, v189
	v_exp_f32_e32 v190, v190
	v_exp_f32_e32 v191, v191
	v_exp_f32_e32 v192, v192
	v_exp_f32_e32 v193, v193
	v_exp_f32_e32 v194, v194
	v_exp_f32_e32 v195, v195
	v_exp_f32_e32 v196, v196
	v_exp_f32_e32 v197, v197
	v_exp_f32_e32 v218, v218
	v_exp_f32_e32 v219, v219
	v_exp_f32_e32 v220, v220
	v_exp_f32_e32 v221, v221
	v_exp_f32_e32 v222, v222
	v_exp_f32_e32 v223, v223
	v_pk_add_f32 v[188:189], v[188:189], v[182:183] op_sel_hi:[1,0]
	v_pk_add_f32 v[190:191], v[190:191], v[182:183] op_sel_hi:[1,0]
	v_pk_add_f32 v[192:193], v[192:193], v[182:183] op_sel_hi:[1,0]
	v_pk_add_f32 v[194:195], v[194:195], v[182:183] op_sel_hi:[1,0]
	v_pk_add_f32 v[196:197], v[196:197], v[182:183] op_sel_hi:[1,0]
	v_pk_add_f32 v[218:219], v[218:219], v[182:183] op_sel_hi:[1,0]
	v_pk_add_f32 v[220:221], v[220:221], v[182:183] op_sel_hi:[1,0]
	v_pk_add_f32 v[222:223], v[222:223], v[182:183] op_sel_hi:[1,0]
	v_rcp_f32_e32 v188, v188
	v_rcp_f32_e32 v189, v189
	v_rcp_f32_e32 v190, v190
	v_rcp_f32_e32 v191, v191
	v_rcp_f32_e32 v192, v192
	v_rcp_f32_e32 v193, v193
	v_rcp_f32_e32 v194, v194
	v_rcp_f32_e32 v195, v195
	v_rcp_f32_e32 v196, v196
	v_rcp_f32_e32 v197, v197
	v_rcp_f32_e32 v218, v218
	v_rcp_f32_e32 v219, v219
	v_rcp_f32_e32 v220, v220
	v_rcp_f32_e32 v221, v221
	v_rcp_f32_e32 v222, v222
	v_rcp_f32_e32 v223, v223
	v_pk_mul_f32 v[188:189], v[146:147], v[188:189]
	v_pk_mul_f32 v[190:191], v[148:149], v[190:191]
	v_pk_mul_f32 v[192:193], v[150:151], v[192:193]
	v_pk_mul_f32 v[194:195], v[152:153], v[194:195]
	v_pk_mul_f32 v[196:197], v[154:155], v[196:197]
	v_pk_mul_f32 v[218:219], v[156:157], v[218:219]
	v_pk_mul_f32 v[220:221], v[158:159], v[220:221]
	v_pk_mul_f32 v[222:223], v[160:161], v[222:223]
	v_pk_mul_f32 v[188:189], v[188:189], v[130:131]
	v_pk_mul_f32 v[190:191], v[190:191], v[132:133]
	v_pk_mul_f32 v[192:193], v[192:193], v[134:135]
	v_pk_mul_f32 v[194:195], v[194:195], v[136:137]
	v_pk_mul_f32 v[196:197], v[196:197], v[138:139]
	v_pk_mul_f32 v[218:219], v[218:219], v[140:141]
	v_pk_mul_f32 v[220:221], v[220:221], v[142:143]
	v_pk_mul_f32 v[222:223], v[222:223], v[144:145]
	v_cvt_pk_bf16_f32 v188, v188, v189
	v_cvt_pk_bf16_f32 v190, v190, v191
	v_cvt_pk_bf16_f32 v192, v192, v193
	v_cvt_pk_bf16_f32 v194, v194, v195
	v_cvt_pk_bf16_f32 v196, v196, v197
	v_cvt_pk_bf16_f32 v218, v218, v219
	v_cvt_pk_bf16_f32 v220, v220, v221
	v_cvt_pk_bf16_f32 v222, v222, v223
	ds_write_b16 v224, v188 offset:6144
	ds_write_b16_d16_hi v237, v188 offset:6208
	ds_write_b16 v224, v190 offset:6272
	ds_write_b16_d16_hi v237, v190 offset:6336
	ds_write_b16 v224, v192 offset:6656
	ds_write_b16_d16_hi v237, v192 offset:6720
	ds_write_b16 v224, v194 offset:6784
	ds_write_b16_d16_hi v237, v194 offset:6848
	ds_write_b16 v224, v196 offset:7168
	ds_write_b16_d16_hi v237, v196 offset:7232
	ds_write_b16 v224, v218 offset:7296
	ds_write_b16_d16_hi v237, v218 offset:7360
	ds_write_b16 v224, v220 offset:7680
	ds_write_b16_d16_hi v237, v220 offset:7744
	ds_write_b16 v224, v222 offset:7808
	ds_write_b16_d16_hi v237, v222 offset:7872
